# v12 plus: residual-add GEMM epilogues (FFN down x2, W_out) de-serialised: X loads prefetched 3 row-chunks ahead into free fragment registers with counted vmcnt waits
# baseline (speedup 1.0000x reference)
; __device__ __forceinline__ unsigned cvtpk(float lo, float hi) { f32x2_t v = {lo, hi}; bf16x2_t b = __builtin_convertvector(v, bf16x2_t); return __builtin_bit_cast(unsigned, b); }
;     __device__ __forceinline__ void operator()(const Acc& acc, const Unit& u, int wr, int wc, int fr, int fq) const {
;         const int row0 = u.pm * BM + wr * 64 + fr, col0 = u.pn * BM + wc * 32 + 8 * fq;
; #pragma unroll
;         for (int ai = 0; ai < 2; ++ai)
; #pragma unroll
;             for (int m = 0; m < 4; ++m) { const int row = row0 + ai * HALF + m * 16; float* rp = X + (size_t)row * DM + col0; const float* ip = Xin + (size_t)row * DM + col0; bf16_t* bp = XB + (size_t)row * DM + col0; float part = 0.f;
; #pragma unroll
;                 for (int bj = 0; bj < 2; ++bj) { f32x4* p = (f32x4*)(rp + bj * HALF); const f32x4* q = (const f32x4*)(ip + bj * HALF); f32x4 a = q[0], b = q[1]; a += acc[ai][bj][m][0] * scale; b += acc[ai][bj][m][1] * scale; p[0] = a; p[1] = b;
;                     *(u32x4*)(bp + bj * HALF) = (u32x4){cvtpk(a[0], a[1]), cvtpk(a[2], a[3]), cvtpk(b[0], b[1]), cvtpk(b[2], b[3])};
;                     part += (a[0] * a[0] + a[1] * a[1]) + (a[2] * a[2] + a[3] * a[3]) + (b[0] * b[0] + b[1] * b[1]) + (b[2] * b[2] + b[3] * b[3]); }
;                 part += __shfl_xor(part, 16); part += __shfl_xor(part, 32);
;                 if (fq == 0) __hip_atomic_fetch_add(SS + row, (u64)(part * SSF), __ATOMIC_RELAXED, __HIP_MEMORY_SCOPE_AGENT); }
.LBB0_173:
	v_lshl_add_u32 v140, s66, 8, v144
	v_lshl_or_b32 v138, s67, 8, v146
	v_ashrrev_i32_e32 v141, 31, v140
	v_ashrrev_i32_e32 v139, 31, v138
	v_lshlrev_b64 v[156:157], 12, v[140:141]
	v_lshlrev_b64 v[142:143], 2, v[138:139]
	v_lshl_add_u64 v[148:149], s[2:3], 0, v[156:157]
	v_lshl_add_u64 v[158:159], v[148:149], 0, v[142:143]
	v_mov_b64_e32 v[218:219], v[158:159]
	global_load_dwordx4 v[166:169], v[218:219], off
	global_load_dwordx4 v[170:173], v[218:219], off offset:16
	global_load_dwordx4 v[174:177], v[218:219], off offset:512
	global_load_dwordx4 v[178:181], v[218:219], off offset:528
	v_mov_b32_e32 v220, 0x10000
	v_mov_b32_e32 v221, 0
	v_lshl_add_u64 v[220:221], v[220:221], 0, v[218:219]
	global_load_dwordx4 v[182:185], v[220:221], off
	global_load_dwordx4 v[186:189], v[220:221], off offset:16
	global_load_dwordx4 v[190:193], v[220:221], off offset:512
	global_load_dwordx4 v[194:197], v[220:221], off offset:528
	v_mov_b32_e32 v220, 0x20000
	v_mov_b32_e32 v221, 0
	v_lshl_add_u64 v[220:221], v[220:221], 0, v[218:219]
	global_load_dwordx4 v[198:201], v[220:221], off
	global_load_dwordx4 v[202:205], v[220:221], off offset:16
	global_load_dwordx4 v[206:209], v[220:221], off offset:512
	global_load_dwordx4 v[210:213], v[220:221], off offset:528
	v_lshlrev_b64 v[162:163], 11, v[140:141]
	v_lshl_add_u64 v[156:157], s[48:49], 0, v[156:157]
	v_lshl_add_u64 v[162:163], s[20:21], 0, v[162:163]
	v_lshl_add_u64 v[164:165], v[156:157], 0, v[142:143]
	v_lshl_add_u64 v[162:163], v[138:139], 1, v[162:163]
	s_waitcnt vmcnt(8)
	v_pk_fma_f32 v[126:127], v[126:127], 0.5, v[168:169] op_sel_hi:[1,0,1]
	v_pk_fma_f32 v[124:125], v[124:125], 0.5, v[166:167] op_sel_hi:[1,0,1]
	v_pk_fma_f32 v[150:151], v[122:123], 0.5, v[172:173] op_sel_hi:[1,0,1]
	v_pk_fma_f32 v[148:149], v[120:121], 0.5, v[170:171] op_sel_hi:[1,0,1]
	v_cvt_pk_bf16_f32 v120, v124, v125
	v_cvt_pk_bf16_f32 v121, v126, v127
	v_cvt_pk_bf16_f32 v122, v148, v149
	v_cvt_pk_bf16_f32 v123, v150, v151
	global_store_dwordx4 v[164:165], v[124:127], off
	global_store_dwordx4 v[164:165], v[148:151], off offset:16
	global_store_dwordx4 v[162:163], v[120:123], off
	s_nop 1
	v_and_b32_e32 v121, 64, v229
	v_xor_b32_e32 v120, 16, v229
	v_add_u32_e32 v121, 64, v121
	v_xor_b32_e32 v122, 32, v229
	v_cmp_lt_i32_e32 vcc, v120, v121
	v_mul_f32_e32 v123, v127, v127
	v_fmac_f32_e32 v123, v126, v126
	v_cndmask_b32_e32 v120, v229, v120, vcc
	v_cmp_lt_i32_e32 vcc, v122, v121
	v_lshlrev_b32_e32 v121, 2, v120
	v_mul_f32_e32 v127, v151, v151
	v_cndmask_b32_e32 v122, v229, v122, vcc
	v_lshlrev_b32_e32 v120, 2, v122
	v_mul_f32_e32 v122, v125, v125
	v_mul_f32_e32 v125, v149, v149
	v_fmac_f32_e32 v122, v124, v124
	v_fmac_f32_e32 v125, v148, v148
	v_add_f32_e32 v122, v122, v123
	v_fmac_f32_e32 v127, v150, v150
	v_add_f32_e32 v122, v125, v122
	v_add_f32_e32 v126, v127, v122
	v_pk_fma_f32 v[118:119], v[118:119], 0.5, v[176:177] op_sel_hi:[1,0,1]
	v_pk_fma_f32 v[116:117], v[116:117], 0.5, v[174:175] op_sel_hi:[1,0,1]
	v_pk_fma_f32 v[122:123], v[112:113], 0.5, v[178:179] op_sel_hi:[1,0,1]
	v_mul_f32_e32 v112, v117, v117
	v_mul_f32_e32 v113, v119, v119
	v_pk_fma_f32 v[124:125], v[114:115], 0.5, v[180:181] op_sel_hi:[1,0,1]
	v_mov_b32_e32 v220, 0x30000
	v_mov_b32_e32 v221, 0
	v_lshl_add_u64 v[220:221], v[220:221], 0, v[218:219]
	global_load_dwordx4 v[166:169], v[220:221], off
	global_load_dwordx4 v[170:173], v[220:221], off offset:16
	global_load_dwordx4 v[174:177], v[220:221], off offset:512
	global_load_dwordx4 v[178:181], v[220:221], off offset:528
	v_mul_f32_e32 v114, v123, v123
	v_fmac_f32_e32 v112, v116, v116
	v_fmac_f32_e32 v113, v118, v118
	v_mul_f32_e32 v115, v125, v125
	v_fmac_f32_e32 v114, v122, v122
	v_add_f32_e32 v112, v112, v113
	v_add_f32_e32 v112, v114, v112
	v_fmac_f32_e32 v115, v124, v124
	v_add_f32_e32 v112, v115, v112
	v_add_f32_e32 v112, v126, v112
	ds_bpermute_b32 v113, v121, v112
	global_store_dwordx4 v[164:165], v[116:119], off offset:512
	global_store_dwordx4 v[164:165], v[122:125], off offset:528
	s_waitcnt lgkmcnt(0)
	v_add_f32_e32 v114, v112, v113
	ds_bpermute_b32 v115, v120, v114
	v_cvt_pk_bf16_f32 v116, v116, v117
	v_cvt_pk_bf16_f32 v117, v118, v119
	v_cvt_pk_bf16_f32 v118, v122, v123
	v_cvt_pk_bf16_f32 v119, v124, v125
	v_lshl_add_u64 v[112:113], v[140:141], 3, s[18:19]
	global_store_dwordx4 v[162:163], v[116:119], off offset:256
	s_and_saveexec_b64 s[16:17], s[42:43]
	s_cbranch_execz .LBB0_175
	s_waitcnt lgkmcnt(0)
	v_add_f32_e32 v114, v114, v115
	v_mul_f32_e32 v114, 0x4b800000, v114
	v_trunc_f32_e32 v114, v114
	v_mul_f32_e32 v115, 0x2f800000, v114
	v_floor_f32_e32 v115, v115
	v_fmac_f32_e32 v114, 0xcf800000, v115
	v_cvt_u32_f32_e32 v114, v114
	v_cvt_u32_f32_e32 v115, v115
	global_atomic_add_x2 v[112:113], v[114:115], off
; __device__ __forceinline__ unsigned cvtpk(float lo, float hi) { f32x2_t v = {lo, hi}; bf16x2_t b = __builtin_convertvector(v, bf16x2_t); return __builtin_bit_cast(unsigned, b); }
;     __device__ __forceinline__ void operator()(const Acc& acc, const Unit& u, int wr, int wc, int fr, int fq) const {
;     ...
;         for (int ai = 0; ai < 2; ++ai)
; #pragma unroll
;             for (int m = 0; m < 4; ++m) { const int row = row0 + ai * HALF + m * 16; float* rp = X + (size_t)row * DM + col0; const float* ip = Xin + (size_t)row * DM + col0; bf16_t* bp = XB + (size_t)row * DM + col0; float part = 0.f;
; #pragma unroll
;                 for (int bj = 0; bj < 2; ++bj) { f32x4* p = (f32x4*)(rp + bj * HALF); const f32x4* q = (const f32x4*)(ip + bj * HALF); f32x4 a = q[0], b = q[1]; a += acc[ai][bj][m][0] * scale; b += acc[ai][bj][m][1] * scale; p[0] = a; p[1] = b;
;                     *(u32x4*)(bp + bj * HALF) = (u32x4){cvtpk(a[0], a[1]), cvtpk(a[2], a[3]), cvtpk(b[0], b[1]), cvtpk(b[2], b[3])};
;                     part += (a[0] * a[0] + a[1] * a[1]) + (a[2] * a[2] + a[3] * a[3]) + (b[0] * b[0] + b[1] * b[1]) + (b[2] * b[2] + b[3] * b[3]); }
;                 part += __shfl_xor(part, 16); part += __shfl_xor(part, 32);
;                 if (fq == 0) __hip_atomic_fetch_add(SS + row, (u64)(part * SSF), __ATOMIC_RELAXED, __HIP_MEMORY_SCOPE_AGENT); }
.LBB0_175:
	s_or_b64 exec, exec, s[16:17]
	v_or_b32_e32 v118, 16, v140
	v_ashrrev_i32_e32 v119, 31, v118
	v_lshlrev_b64 v[126:127], 12, v[118:119]
	s_waitcnt lgkmcnt(0)
	v_lshl_add_u64 v[114:115], s[2:3], 0, v[126:127]
	v_lshl_add_u64 v[148:149], v[114:115], 0, v[142:143]
	v_lshlrev_b64 v[118:119], 11, v[118:119]
	v_lshl_add_u64 v[126:127], s[48:49], 0, v[126:127]
	v_lshl_add_u64 v[118:119], s[20:21], 0, v[118:119]
	v_lshl_add_u64 v[126:127], v[126:127], 0, v[142:143]
	v_lshl_add_u64 v[118:119], v[138:139], 1, v[118:119]
	s_waitcnt vmcnt(15)
	v_pk_fma_f32 v[110:111], v[110:111], 0.5, v[184:185] op_sel_hi:[1,0,1]
	v_pk_fma_f32 v[108:109], v[108:109], 0.5, v[182:183] op_sel_hi:[1,0,1]
	v_pk_fma_f32 v[106:107], v[106:107], 0.5, v[188:189] op_sel_hi:[1,0,1]
	v_pk_fma_f32 v[104:105], v[104:105], 0.5, v[186:187] op_sel_hi:[1,0,1]
	v_cvt_pk_bf16_f32 v114, v108, v109
	v_cvt_pk_bf16_f32 v115, v110, v111
	v_cvt_pk_bf16_f32 v116, v104, v105
	v_cvt_pk_bf16_f32 v117, v106, v107
	global_store_dwordx4 v[126:127], v[108:111], off
	global_store_dwordx4 v[126:127], v[104:107], off offset:16
	global_store_dwordx4 v[118:119], v[114:117], off
	s_nop 1
	v_mul_f32_e32 v109, v109, v109
	v_mul_f32_e32 v111, v111, v111
	v_mul_f32_e32 v105, v105, v105
	v_fmac_f32_e32 v109, v108, v108
	v_fmac_f32_e32 v111, v110, v110
	v_mul_f32_e32 v107, v107, v107
	v_fmac_f32_e32 v105, v104, v104
	v_add_f32_e32 v104, v109, v111
	v_fmac_f32_e32 v107, v106, v106
	v_add_f32_e32 v104, v105, v104
	v_add_f32_e32 v108, v107, v104
	v_pk_fma_f32 v[102:103], v[102:103], 0.5, v[192:193] op_sel_hi:[1,0,1]
	v_pk_fma_f32 v[100:101], v[100:101], 0.5, v[190:191] op_sel_hi:[1,0,1]
	v_pk_fma_f32 v[104:105], v[96:97], 0.5, v[194:195] op_sel_hi:[1,0,1]
	v_mul_f32_e32 v96, v101, v101
	v_mul_f32_e32 v97, v103, v103
	v_pk_fma_f32 v[106:107], v[98:99], 0.5, v[196:197] op_sel_hi:[1,0,1]
	v_mov_b32_e32 v220, 0x80000
	v_mov_b32_e32 v221, 0
	v_lshl_add_u64 v[220:221], v[220:221], 0, v[218:219]
	global_load_dwordx4 v[182:185], v[220:221], off
	global_load_dwordx4 v[186:189], v[220:221], off offset:16
	global_load_dwordx4 v[190:193], v[220:221], off offset:512
	global_load_dwordx4 v[194:197], v[220:221], off offset:528
	v_mul_f32_e32 v98, v105, v105
	v_fmac_f32_e32 v96, v100, v100
	v_fmac_f32_e32 v97, v102, v102
	v_mul_f32_e32 v99, v107, v107
	v_fmac_f32_e32 v98, v104, v104
	v_add_f32_e32 v96, v96, v97
	v_add_f32_e32 v96, v98, v96
	v_fmac_f32_e32 v99, v106, v106
	v_add_f32_e32 v96, v99, v96
	v_add_f32_e32 v96, v108, v96
	ds_bpermute_b32 v97, v121, v96
	global_store_dwordx4 v[126:127], v[100:103], off offset:512
	global_store_dwordx4 v[126:127], v[104:107], off offset:528
	v_cvt_pk_bf16_f32 v98, v100, v101
	v_cvt_pk_bf16_f32 v99, v102, v103
	v_cvt_pk_bf16_f32 v100, v104, v105
	s_waitcnt lgkmcnt(0)
	v_add_f32_e32 v96, v96, v97
	ds_bpermute_b32 v97, v120, v96
	v_cvt_pk_bf16_f32 v101, v106, v107
	global_store_dwordx4 v[118:119], v[98:101], off offset:256
	s_and_saveexec_b64 s[16:17], s[42:43]
	s_cbranch_execz .LBB0_177
	s_waitcnt lgkmcnt(0)
	v_add_f32_e32 v96, v96, v97
	v_mul_f32_e32 v96, 0x4b800000, v96
	v_trunc_f32_e32 v96, v96
	v_mul_f32_e32 v97, 0x2f800000, v96
	v_floor_f32_e32 v97, v97
	v_fmac_f32_e32 v96, 0xcf800000, v97
	v_cvt_u32_f32_e32 v96, v96
	v_cvt_u32_f32_e32 v97, v97
	global_atomic_add_x2 v[112:113], v[96:97], off offset:128
.LBB0_177:
	s_or_b64 exec, exec, s[16:17]
	v_or_b32_e32 v104, 32, v140
	v_ashrrev_i32_e32 v105, 31, v104
	v_lshlrev_b64 v[106:107], 12, v[104:105]
	s_waitcnt lgkmcnt(0)
	v_lshl_add_u64 v[96:97], s[2:3], 0, v[106:107]
	v_lshl_add_u64 v[108:109], v[96:97], 0, v[142:143]
	v_lshlrev_b64 v[104:105], 11, v[104:105]
	v_lshl_add_u64 v[106:107], s[48:49], 0, v[106:107]
	v_lshl_add_u64 v[104:105], s[20:21], 0, v[104:105]
	v_lshl_add_u64 v[106:107], v[106:107], 0, v[142:143]
	v_lshl_add_u64 v[104:105], v[138:139], 1, v[104:105]
	s_waitcnt vmcnt(22)
	v_pk_fma_f32 v[94:95], v[94:95], 0.5, v[200:201] op_sel_hi:[1,0,1]
	v_pk_fma_f32 v[92:93], v[92:93], 0.5, v[198:199] op_sel_hi:[1,0,1]
	v_pk_fma_f32 v[90:91], v[90:91], 0.5, v[204:205] op_sel_hi:[1,0,1]
	v_pk_fma_f32 v[88:89], v[88:89], 0.5, v[202:203] op_sel_hi:[1,0,1]
	v_cvt_pk_bf16_f32 v96, v92, v93
	v_cvt_pk_bf16_f32 v97, v94, v95
	v_cvt_pk_bf16_f32 v98, v88, v89
	v_cvt_pk_bf16_f32 v99, v90, v91
	global_store_dwordx4 v[106:107], v[92:95], off
	global_store_dwordx4 v[106:107], v[88:91], off offset:16
	global_store_dwordx4 v[104:105], v[96:99], off
	s_nop 1
	v_mul_f32_e32 v93, v93, v93
	v_mul_f32_e32 v95, v95, v95
	v_mul_f32_e32 v89, v89, v89
	v_fmac_f32_e32 v93, v92, v92
	v_fmac_f32_e32 v95, v94, v94
	v_mul_f32_e32 v91, v91, v91
	v_fmac_f32_e32 v89, v88, v88
	v_add_f32_e32 v88, v93, v95
	v_fmac_f32_e32 v91, v90, v90
	v_add_f32_e32 v88, v89, v88
	v_add_f32_e32 v92, v91, v88
	v_pk_fma_f32 v[86:87], v[86:87], 0.5, v[208:209] op_sel_hi:[1,0,1]
	v_pk_fma_f32 v[84:85], v[84:85], 0.5, v[206:207] op_sel_hi:[1,0,1]
	v_pk_fma_f32 v[88:89], v[80:81], 0.5, v[210:211] op_sel_hi:[1,0,1]
	v_mul_f32_e32 v80, v85, v85
	v_mul_f32_e32 v81, v87, v87
	v_pk_fma_f32 v[90:91], v[82:83], 0.5, v[212:213] op_sel_hi:[1,0,1]
	v_mov_b32_e32 v220, 0x90000
	v_mov_b32_e32 v221, 0
	v_lshl_add_u64 v[220:221], v[220:221], 0, v[218:219]
	global_load_dwordx4 v[198:201], v[220:221], off
	global_load_dwordx4 v[202:205], v[220:221], off offset:16
	global_load_dwordx4 v[206:209], v[220:221], off offset:512
	global_load_dwordx4 v[210:213], v[220:221], off offset:528
	v_mul_f32_e32 v82, v89, v89
	v_fmac_f32_e32 v80, v84, v84
	v_fmac_f32_e32 v81, v86, v86
	v_mul_f32_e32 v83, v91, v91
	v_fmac_f32_e32 v82, v88, v88
	v_add_f32_e32 v80, v80, v81
	v_add_f32_e32 v80, v82, v80
	v_fmac_f32_e32 v83, v90, v90
	v_add_f32_e32 v80, v83, v80
	v_add_f32_e32 v80, v92, v80
	ds_bpermute_b32 v81, v121, v80
	global_store_dwordx4 v[106:107], v[84:87], off offset:512
	global_store_dwordx4 v[106:107], v[88:91], off offset:528
	v_cvt_pk_bf16_f32 v82, v84, v85
	v_cvt_pk_bf16_f32 v83, v86, v87
	v_cvt_pk_bf16_f32 v84, v88, v89
	s_waitcnt lgkmcnt(0)
	v_add_f32_e32 v80, v80, v81
	ds_bpermute_b32 v81, v120, v80
	v_cvt_pk_bf16_f32 v85, v90, v91
	global_store_dwordx4 v[104:105], v[82:85], off offset:256
	s_and_saveexec_b64 s[16:17], s[42:43]
	s_cbranch_execz .LBB0_179
	s_waitcnt lgkmcnt(0)
	v_add_f32_e32 v80, v80, v81
	v_mul_f32_e32 v80, 0x4b800000, v80
	v_trunc_f32_e32 v80, v80
	v_mul_f32_e32 v81, 0x2f800000, v80
	v_floor_f32_e32 v81, v81
	v_fmac_f32_e32 v80, 0xcf800000, v81
	v_cvt_u32_f32_e32 v80, v80
	v_cvt_u32_f32_e32 v81, v81
	global_atomic_add_x2 v[112:113], v[80:81], off offset:256
; __device__ __forceinline__ unsigned cvtpk(float lo, float hi) { f32x2_t v = {lo, hi}; bf16x2_t b = __builtin_convertvector(v, bf16x2_t); return __builtin_bit_cast(unsigned, b); }
;     __device__ __forceinline__ void operator()(const Acc& acc, const Unit& u, int wr, int wc, int fr, int fq) const {
;     ...
;         for (int ai = 0; ai < 2; ++ai)
; #pragma unroll
;             for (int m = 0; m < 4; ++m) { const int row = row0 + ai * HALF + m * 16; float* rp = X + (size_t)row * DM + col0; const float* ip = Xin + (size_t)row * DM + col0; bf16_t* bp = XB + (size_t)row * DM + col0; float part = 0.f;
; #pragma unroll
;                 for (int bj = 0; bj < 2; ++bj) { f32x4* p = (f32x4*)(rp + bj * HALF); const f32x4* q = (const f32x4*)(ip + bj * HALF); f32x4 a = q[0], b = q[1]; a += acc[ai][bj][m][0] * scale; b += acc[ai][bj][m][1] * scale; p[0] = a; p[1] = b;
;                     *(u32x4*)(bp + bj * HALF) = (u32x4){cvtpk(a[0], a[1]), cvtpk(a[2], a[3]), cvtpk(b[0], b[1]), cvtpk(b[2], b[3])};
;                     part += (a[0] * a[0] + a[1] * a[1]) + (a[2] * a[2] + a[3] * a[3]) + (b[0] * b[0] + b[1] * b[1]) + (b[2] * b[2] + b[3] * b[3]); }
;                 part += __shfl_xor(part, 16); part += __shfl_xor(part, 32);
;                 if (fq == 0) __hip_atomic_fetch_add(SS + row, (u64)(part * SSF), __ATOMIC_RELAXED, __HIP_MEMORY_SCOPE_AGENT); }
.LBB0_179:
	s_or_b64 exec, exec, s[16:17]
	v_or_b32_e32 v88, 48, v140
	v_ashrrev_i32_e32 v89, 31, v88
	v_lshlrev_b64 v[90:91], 12, v[88:89]
	s_waitcnt lgkmcnt(0)
	v_lshl_add_u64 v[80:81], s[2:3], 0, v[90:91]
	v_lshl_add_u64 v[92:93], v[80:81], 0, v[142:143]
	v_lshlrev_b64 v[88:89], 11, v[88:89]
	v_lshl_add_u64 v[90:91], s[48:49], 0, v[90:91]
	v_lshl_add_u64 v[88:89], s[20:21], 0, v[88:89]
	v_lshl_add_u64 v[90:91], v[90:91], 0, v[142:143]
	v_lshl_add_u64 v[88:89], v[138:139], 1, v[88:89]
	s_waitcnt vmcnt(26)
	v_pk_fma_f32 v[78:79], v[78:79], 0.5, v[168:169] op_sel_hi:[1,0,1]
	v_pk_fma_f32 v[76:77], v[76:77], 0.5, v[166:167] op_sel_hi:[1,0,1]
	v_pk_fma_f32 v[74:75], v[74:75], 0.5, v[172:173] op_sel_hi:[1,0,1]
	v_pk_fma_f32 v[72:73], v[72:73], 0.5, v[170:171] op_sel_hi:[1,0,1]
	v_cvt_pk_bf16_f32 v80, v76, v77
	v_cvt_pk_bf16_f32 v81, v78, v79
	v_cvt_pk_bf16_f32 v82, v72, v73
	v_cvt_pk_bf16_f32 v83, v74, v75
	global_store_dwordx4 v[90:91], v[76:79], off
	global_store_dwordx4 v[90:91], v[72:75], off offset:16
	global_store_dwordx4 v[88:89], v[80:83], off
	s_nop 1
	v_mul_f32_e32 v77, v77, v77
	v_mul_f32_e32 v79, v79, v79
	v_mul_f32_e32 v73, v73, v73
	v_fmac_f32_e32 v77, v76, v76
	v_fmac_f32_e32 v79, v78, v78
	v_mul_f32_e32 v75, v75, v75
	v_fmac_f32_e32 v73, v72, v72
	v_add_f32_e32 v72, v77, v79
	v_fmac_f32_e32 v75, v74, v74
	v_add_f32_e32 v72, v73, v72
	v_add_f32_e32 v76, v75, v72
	v_pk_fma_f32 v[70:71], v[70:71], 0.5, v[176:177] op_sel_hi:[1,0,1]
	v_pk_fma_f32 v[68:69], v[68:69], 0.5, v[174:175] op_sel_hi:[1,0,1]
	v_pk_fma_f32 v[72:73], v[64:65], 0.5, v[178:179] op_sel_hi:[1,0,1]
	v_mul_f32_e32 v64, v69, v69
	v_mul_f32_e32 v65, v71, v71
	v_pk_fma_f32 v[74:75], v[66:67], 0.5, v[180:181] op_sel_hi:[1,0,1]
	v_mov_b32_e32 v220, 0xa0000
	v_mov_b32_e32 v221, 0
	v_lshl_add_u64 v[220:221], v[220:221], 0, v[218:219]
	global_load_dwordx4 v[166:169], v[220:221], off
	global_load_dwordx4 v[170:173], v[220:221], off offset:16
	global_load_dwordx4 v[174:177], v[220:221], off offset:512
	global_load_dwordx4 v[178:181], v[220:221], off offset:528
	v_mul_f32_e32 v66, v73, v73
	v_fmac_f32_e32 v64, v68, v68
	v_fmac_f32_e32 v65, v70, v70
	v_mul_f32_e32 v67, v75, v75
	v_fmac_f32_e32 v66, v72, v72
	v_add_f32_e32 v64, v64, v65
	v_add_f32_e32 v64, v66, v64
	v_fmac_f32_e32 v67, v74, v74
	v_add_f32_e32 v64, v67, v64
	v_add_f32_e32 v64, v76, v64
	ds_bpermute_b32 v65, v121, v64
	global_store_dwordx4 v[90:91], v[68:71], off offset:512
	global_store_dwordx4 v[90:91], v[72:75], off offset:528
	v_cvt_pk_bf16_f32 v66, v68, v69
	v_cvt_pk_bf16_f32 v67, v70, v71
	v_cvt_pk_bf16_f32 v68, v72, v73
	s_waitcnt lgkmcnt(0)
	v_add_f32_e32 v64, v64, v65
	ds_bpermute_b32 v65, v120, v64
	v_cvt_pk_bf16_f32 v69, v74, v75
	global_store_dwordx4 v[88:89], v[66:69], off offset:256
	s_and_saveexec_b64 s[16:17], s[42:43]
	s_cbranch_execz .LBB0_181
	s_waitcnt lgkmcnt(0)
	v_add_f32_e32 v64, v64, v65
	v_mul_f32_e32 v64, 0x4b800000, v64
	v_trunc_f32_e32 v64, v64
	v_mul_f32_e32 v65, 0x2f800000, v64
	v_floor_f32_e32 v65, v65
	v_fmac_f32_e32 v64, 0xcf800000, v65
	v_cvt_u32_f32_e32 v64, v64
	v_cvt_u32_f32_e32 v65, v65
	global_atomic_add_x2 v[112:113], v[64:65], off offset:384
.LBB0_181:
	s_or_b64 exec, exec, s[16:17]
	v_add_u32_e32 v72, 0x80, v140
	v_ashrrev_i32_e32 v73, 31, v72
	v_lshlrev_b64 v[74:75], 12, v[72:73]
	s_waitcnt lgkmcnt(0)
	v_lshl_add_u64 v[64:65], s[2:3], 0, v[74:75]
	v_lshl_add_u64 v[76:77], v[64:65], 0, v[142:143]
	v_lshlrev_b64 v[72:73], 11, v[72:73]
	v_lshl_add_u64 v[74:75], s[48:49], 0, v[74:75]
	v_lshl_add_u64 v[72:73], s[20:21], 0, v[72:73]
	v_lshl_add_u64 v[74:75], v[74:75], 0, v[142:143]
	v_lshl_add_u64 v[72:73], v[138:139], 1, v[72:73]
	s_waitcnt vmcnt(26)
	v_pk_fma_f32 v[62:63], v[62:63], 0.5, v[184:185] op_sel_hi:[1,0,1]
	v_pk_fma_f32 v[60:61], v[60:61], 0.5, v[182:183] op_sel_hi:[1,0,1]
	v_pk_fma_f32 v[58:59], v[58:59], 0.5, v[188:189] op_sel_hi:[1,0,1]
	v_pk_fma_f32 v[56:57], v[56:57], 0.5, v[186:187] op_sel_hi:[1,0,1]
	v_cvt_pk_bf16_f32 v64, v60, v61
	v_cvt_pk_bf16_f32 v65, v62, v63
	v_cvt_pk_bf16_f32 v66, v56, v57
	v_cvt_pk_bf16_f32 v67, v58, v59
	global_store_dwordx4 v[74:75], v[60:63], off
	global_store_dwordx4 v[74:75], v[56:59], off offset:16
	global_store_dwordx4 v[72:73], v[64:67], off
	s_nop 1
	v_mul_f32_e32 v61, v61, v61
	v_mul_f32_e32 v63, v63, v63
	v_mul_f32_e32 v57, v57, v57
	v_fmac_f32_e32 v61, v60, v60
	v_fmac_f32_e32 v63, v62, v62
	v_mul_f32_e32 v59, v59, v59
	v_fmac_f32_e32 v57, v56, v56
	v_add_f32_e32 v56, v61, v63
	v_fmac_f32_e32 v59, v58, v58
	v_add_f32_e32 v56, v57, v56
	v_add_f32_e32 v60, v59, v56
	v_pk_fma_f32 v[54:55], v[54:55], 0.5, v[192:193] op_sel_hi:[1,0,1]
	v_pk_fma_f32 v[52:53], v[52:53], 0.5, v[190:191] op_sel_hi:[1,0,1]
	v_pk_fma_f32 v[56:57], v[48:49], 0.5, v[194:195] op_sel_hi:[1,0,1]
	v_mul_f32_e32 v48, v53, v53
	v_mul_f32_e32 v49, v55, v55
	v_pk_fma_f32 v[58:59], v[50:51], 0.5, v[196:197] op_sel_hi:[1,0,1]
	v_mov_b32_e32 v220, 0xb0000
	v_mov_b32_e32 v221, 0
	v_lshl_add_u64 v[220:221], v[220:221], 0, v[218:219]
	global_load_dwordx4 v[182:185], v[220:221], off
	global_load_dwordx4 v[186:189], v[220:221], off offset:16
	global_load_dwordx4 v[190:193], v[220:221], off offset:512
	global_load_dwordx4 v[194:197], v[220:221], off offset:528
	v_mul_f32_e32 v50, v57, v57
	v_fmac_f32_e32 v48, v52, v52
	v_fmac_f32_e32 v49, v54, v54
	v_mul_f32_e32 v51, v59, v59
	v_fmac_f32_e32 v50, v56, v56
	v_add_f32_e32 v48, v48, v49
	v_add_f32_e32 v48, v50, v48
	v_fmac_f32_e32 v51, v58, v58
	v_add_f32_e32 v48, v51, v48
	v_add_f32_e32 v48, v60, v48
	ds_bpermute_b32 v49, v121, v48
	global_store_dwordx4 v[74:75], v[52:55], off offset:512
	global_store_dwordx4 v[74:75], v[56:59], off offset:528
	v_cvt_pk_bf16_f32 v50, v52, v53
	v_cvt_pk_bf16_f32 v51, v54, v55
	v_cvt_pk_bf16_f32 v52, v56, v57
	s_waitcnt lgkmcnt(0)
	v_add_f32_e32 v48, v48, v49
	ds_bpermute_b32 v49, v120, v48
	v_cvt_pk_bf16_f32 v53, v58, v59
	global_store_dwordx4 v[72:73], v[50:53], off offset:256
	s_and_saveexec_b64 s[16:17], s[42:43]
	s_cbranch_execz .LBB0_183
	s_waitcnt lgkmcnt(0)
	v_add_f32_e32 v48, v48, v49
	v_mul_f32_e32 v48, 0x4b800000, v48
	v_trunc_f32_e32 v48, v48
	v_mul_f32_e32 v49, 0x2f800000, v48
	v_floor_f32_e32 v49, v49
	v_fmac_f32_e32 v48, 0xcf800000, v49
	v_cvt_u32_f32_e32 v48, v48
	v_cvt_u32_f32_e32 v49, v49
	global_atomic_add_x2 v[112:113], v[48:49], off offset:1024
; __device__ __forceinline__ unsigned cvtpk(float lo, float hi) { f32x2_t v = {lo, hi}; bf16x2_t b = __builtin_convertvector(v, bf16x2_t); return __builtin_bit_cast(unsigned, b); }
;     __device__ __forceinline__ void operator()(const Acc& acc, const Unit& u, int wr, int wc, int fr, int fq) const {
;     ...
;         for (int ai = 0; ai < 2; ++ai)
; #pragma unroll
;             for (int m = 0; m < 4; ++m) { const int row = row0 + ai * HALF + m * 16; float* rp = X + (size_t)row * DM + col0; const float* ip = Xin + (size_t)row * DM + col0; bf16_t* bp = XB + (size_t)row * DM + col0; float part = 0.f;
; #pragma unroll
;                 for (int bj = 0; bj < 2; ++bj) { f32x4* p = (f32x4*)(rp + bj * HALF); const f32x4* q = (const f32x4*)(ip + bj * HALF); f32x4 a = q[0], b = q[1]; a += acc[ai][bj][m][0] * scale; b += acc[ai][bj][m][1] * scale; p[0] = a; p[1] = b;
;                     *(u32x4*)(bp + bj * HALF) = (u32x4){cvtpk(a[0], a[1]), cvtpk(a[2], a[3]), cvtpk(b[0], b[1]), cvtpk(b[2], b[3])};
;                     part += (a[0] * a[0] + a[1] * a[1]) + (a[2] * a[2] + a[3] * a[3]) + (b[0] * b[0] + b[1] * b[1]) + (b[2] * b[2] + b[3] * b[3]); }
;                 part += __shfl_xor(part, 16); part += __shfl_xor(part, 32);
;                 if (fq == 0) __hip_atomic_fetch_add(SS + row, (u64)(part * SSF), __ATOMIC_RELAXED, __HIP_MEMORY_SCOPE_AGENT); }
.LBB0_183:
	s_or_b64 exec, exec, s[16:17]
	v_add_u32_e32 v56, 0x90, v140
	v_ashrrev_i32_e32 v57, 31, v56
	v_lshlrev_b64 v[58:59], 12, v[56:57]
	s_waitcnt lgkmcnt(0)
	v_lshl_add_u64 v[48:49], s[2:3], 0, v[58:59]
	v_lshl_add_u64 v[60:61], v[48:49], 0, v[142:143]
	v_lshlrev_b64 v[56:57], 11, v[56:57]
	v_lshl_add_u64 v[58:59], s[48:49], 0, v[58:59]
	v_lshl_add_u64 v[56:57], s[20:21], 0, v[56:57]
	v_lshl_add_u64 v[58:59], v[58:59], 0, v[142:143]
	v_lshl_add_u64 v[56:57], v[138:139], 1, v[56:57]
	s_waitcnt vmcnt(26)
	v_pk_fma_f32 v[46:47], v[46:47], 0.5, v[200:201] op_sel_hi:[1,0,1]
	v_pk_fma_f32 v[44:45], v[44:45], 0.5, v[198:199] op_sel_hi:[1,0,1]
	v_pk_fma_f32 v[42:43], v[42:43], 0.5, v[204:205] op_sel_hi:[1,0,1]
	v_pk_fma_f32 v[40:41], v[40:41], 0.5, v[202:203] op_sel_hi:[1,0,1]
	v_cvt_pk_bf16_f32 v48, v44, v45
	v_cvt_pk_bf16_f32 v49, v46, v47
	v_cvt_pk_bf16_f32 v50, v40, v41
	v_cvt_pk_bf16_f32 v51, v42, v43
	global_store_dwordx4 v[58:59], v[44:47], off
	global_store_dwordx4 v[58:59], v[40:43], off offset:16
	global_store_dwordx4 v[56:57], v[48:51], off
	s_nop 1
	v_mul_f32_e32 v45, v45, v45
	v_mul_f32_e32 v47, v47, v47
	v_mul_f32_e32 v41, v41, v41
	v_fmac_f32_e32 v45, v44, v44
	v_fmac_f32_e32 v47, v46, v46
	v_mul_f32_e32 v43, v43, v43
	v_fmac_f32_e32 v41, v40, v40
	v_add_f32_e32 v40, v45, v47
	v_fmac_f32_e32 v43, v42, v42
	v_add_f32_e32 v40, v41, v40
	v_add_f32_e32 v44, v43, v40
	v_pk_fma_f32 v[38:39], v[38:39], 0.5, v[208:209] op_sel_hi:[1,0,1]
	v_pk_fma_f32 v[36:37], v[36:37], 0.5, v[206:207] op_sel_hi:[1,0,1]
	v_pk_fma_f32 v[40:41], v[32:33], 0.5, v[210:211] op_sel_hi:[1,0,1]
	v_mul_f32_e32 v32, v37, v37
	v_mul_f32_e32 v33, v39, v39
	v_pk_fma_f32 v[42:43], v[34:35], 0.5, v[212:213] op_sel_hi:[1,0,1]
	v_mul_f32_e32 v34, v41, v41
	v_fmac_f32_e32 v32, v36, v36
	v_fmac_f32_e32 v33, v38, v38
	v_mul_f32_e32 v35, v43, v43
	v_fmac_f32_e32 v34, v40, v40
	v_add_f32_e32 v32, v32, v33
	v_add_f32_e32 v32, v34, v32
	v_fmac_f32_e32 v35, v42, v42
	v_add_f32_e32 v32, v35, v32
	v_add_f32_e32 v32, v44, v32
	ds_bpermute_b32 v33, v121, v32
	global_store_dwordx4 v[58:59], v[36:39], off offset:512
	global_store_dwordx4 v[58:59], v[40:43], off offset:528
	v_cvt_pk_bf16_f32 v34, v36, v37
	v_cvt_pk_bf16_f32 v35, v38, v39
	v_cvt_pk_bf16_f32 v36, v40, v41
	s_waitcnt lgkmcnt(0)
	v_add_f32_e32 v32, v32, v33
	ds_bpermute_b32 v33, v120, v32
	v_cvt_pk_bf16_f32 v37, v42, v43
	global_store_dwordx4 v[56:57], v[34:37], off offset:256
	s_and_saveexec_b64 s[16:17], s[42:43]
	s_cbranch_execz .LBB0_185
	s_waitcnt lgkmcnt(0)
	v_add_f32_e32 v32, v32, v33
	v_mul_f32_e32 v32, 0x4b800000, v32
	v_trunc_f32_e32 v32, v32
	v_mul_f32_e32 v33, 0x2f800000, v32
	v_floor_f32_e32 v33, v33
	v_fmac_f32_e32 v32, 0xcf800000, v33
	v_cvt_u32_f32_e32 v32, v32
	v_cvt_u32_f32_e32 v33, v33
	global_atomic_add_x2 v[112:113], v[32:33], off offset:1152
; __device__ __forceinline__ unsigned cvtpk(float lo, float hi) { f32x2_t v = {lo, hi}; bf16x2_t b = __builtin_convertvector(v, bf16x2_t); return __builtin_bit_cast(unsigned, b); }
;     __device__ __forceinline__ void operator()(const Acc& acc, const Unit& u, int wr, int wc, int fr, int fq) const {
;     ...
;         for (int ai = 0; ai < 2; ++ai)
; #pragma unroll
;             for (int m = 0; m < 4; ++m) { const int row = row0 + ai * HALF + m * 16; float* rp = X + (size_t)row * DM + col0; const float* ip = Xin + (size_t)row * DM + col0; bf16_t* bp = XB + (size_t)row * DM + col0; float part = 0.f;
; #pragma unroll
;                 for (int bj = 0; bj < 2; ++bj) { f32x4* p = (f32x4*)(rp + bj * HALF); const f32x4* q = (const f32x4*)(ip + bj * HALF); f32x4 a = q[0], b = q[1]; a += acc[ai][bj][m][0] * scale; b += acc[ai][bj][m][1] * scale; p[0] = a; p[1] = b;
;                     *(u32x4*)(bp + bj * HALF) = (u32x4){cvtpk(a[0], a[1]), cvtpk(a[2], a[3]), cvtpk(b[0], b[1]), cvtpk(b[2], b[3])};
;                     part += (a[0] * a[0] + a[1] * a[1]) + (a[2] * a[2] + a[3] * a[3]) + (b[0] * b[0] + b[1] * b[1]) + (b[2] * b[2] + b[3] * b[3]); }
;                 part += __shfl_xor(part, 16); part += __shfl_xor(part, 32);
;                 if (fq == 0) __hip_atomic_fetch_add(SS + row, (u64)(part * SSF), __ATOMIC_RELAXED, __HIP_MEMORY_SCOPE_AGENT); }
.LBB0_185:
	s_or_b64 exec, exec, s[16:17]
	v_add_u32_e32 v40, 0xa0, v140
	v_ashrrev_i32_e32 v41, 31, v40
	v_lshlrev_b64 v[42:43], 12, v[40:41]
	s_waitcnt lgkmcnt(0)
	v_lshl_add_u64 v[32:33], s[2:3], 0, v[42:43]
	v_lshl_add_u64 v[44:45], v[32:33], 0, v[142:143]
	v_lshlrev_b64 v[40:41], 11, v[40:41]
	v_lshl_add_u64 v[42:43], s[48:49], 0, v[42:43]
	v_lshl_add_u64 v[40:41], s[20:21], 0, v[40:41]
	v_lshl_add_u64 v[42:43], v[42:43], 0, v[142:143]
	v_lshl_add_u64 v[40:41], v[138:139], 1, v[40:41]
	s_waitcnt vmcnt(22)
	v_pk_fma_f32 v[30:31], v[30:31], 0.5, v[168:169] op_sel_hi:[1,0,1]
	v_pk_fma_f32 v[28:29], v[28:29], 0.5, v[166:167] op_sel_hi:[1,0,1]
	v_pk_fma_f32 v[26:27], v[26:27], 0.5, v[172:173] op_sel_hi:[1,0,1]
	v_pk_fma_f32 v[24:25], v[24:25], 0.5, v[170:171] op_sel_hi:[1,0,1]
	v_cvt_pk_bf16_f32 v32, v28, v29
	v_cvt_pk_bf16_f32 v33, v30, v31
	v_cvt_pk_bf16_f32 v34, v24, v25
	v_cvt_pk_bf16_f32 v35, v26, v27
	global_store_dwordx4 v[42:43], v[28:31], off
	global_store_dwordx4 v[42:43], v[24:27], off offset:16
	global_store_dwordx4 v[40:41], v[32:35], off
	s_nop 1
	v_mul_f32_e32 v29, v29, v29
	v_mul_f32_e32 v31, v31, v31
	v_mul_f32_e32 v25, v25, v25
	v_fmac_f32_e32 v29, v28, v28
	v_fmac_f32_e32 v31, v30, v30
	v_mul_f32_e32 v27, v27, v27
	v_fmac_f32_e32 v25, v24, v24
	v_add_f32_e32 v24, v29, v31
	v_fmac_f32_e32 v27, v26, v26
	v_add_f32_e32 v24, v25, v24
	v_add_f32_e32 v28, v27, v24
	v_pk_fma_f32 v[22:23], v[22:23], 0.5, v[176:177] op_sel_hi:[1,0,1]
	v_pk_fma_f32 v[20:21], v[20:21], 0.5, v[174:175] op_sel_hi:[1,0,1]
	v_pk_fma_f32 v[24:25], v[16:17], 0.5, v[178:179] op_sel_hi:[1,0,1]
	v_mul_f32_e32 v16, v21, v21
	v_mul_f32_e32 v17, v23, v23
	v_pk_fma_f32 v[26:27], v[18:19], 0.5, v[180:181] op_sel_hi:[1,0,1]
	v_mul_f32_e32 v18, v25, v25
	v_fmac_f32_e32 v16, v20, v20
	v_fmac_f32_e32 v17, v22, v22
	v_mul_f32_e32 v19, v27, v27
	v_fmac_f32_e32 v18, v24, v24
	v_add_f32_e32 v16, v16, v17
	v_add_f32_e32 v16, v18, v16
	v_fmac_f32_e32 v19, v26, v26
	v_add_f32_e32 v16, v19, v16
	v_add_f32_e32 v16, v28, v16
	ds_bpermute_b32 v17, v121, v16
	global_store_dwordx4 v[42:43], v[20:23], off offset:512
	global_store_dwordx4 v[42:43], v[24:27], off offset:528
	v_cvt_pk_bf16_f32 v18, v20, v21
	v_cvt_pk_bf16_f32 v19, v22, v23
	v_cvt_pk_bf16_f32 v20, v24, v25
	s_waitcnt lgkmcnt(0)
	v_add_f32_e32 v16, v16, v17
	ds_bpermute_b32 v17, v120, v16
	v_cvt_pk_bf16_f32 v21, v26, v27
	global_store_dwordx4 v[40:41], v[18:21], off offset:256
	s_and_saveexec_b64 s[16:17], s[42:43]
	s_cbranch_execz .LBB0_187
	s_waitcnt lgkmcnt(0)
	v_add_f32_e32 v16, v16, v17
	v_mul_f32_e32 v16, 0x4b800000, v16
	v_trunc_f32_e32 v16, v16
	v_mul_f32_e32 v17, 0x2f800000, v16
	v_floor_f32_e32 v17, v17
	v_fmac_f32_e32 v16, 0xcf800000, v17
	v_cvt_u32_f32_e32 v16, v16
	v_cvt_u32_f32_e32 v17, v17
	global_atomic_add_x2 v[112:113], v[16:17], off offset:1280
.LBB0_187:
	s_or_b64 exec, exec, s[16:17]
	v_add_u32_e32 v16, 0xb0, v140
	s_waitcnt lgkmcnt(0)
	v_ashrrev_i32_e32 v17, 31, v16
	v_lshlrev_b64 v[18:19], 12, v[16:17]
	v_lshl_add_u64 v[20:21], s[48:49], 0, v[18:19]
	v_lshl_add_u64 v[18:19], s[2:3], 0, v[18:19]
	v_lshlrev_b64 v[16:17], 11, v[16:17]
	v_lshl_add_u64 v[26:27], v[18:19], 0, v[142:143]
	v_lshl_add_u64 v[16:17], s[20:21], 0, v[16:17]
	v_lshl_add_u64 v[24:25], v[20:21], 0, v[142:143]
	v_lshl_add_u64 v[28:29], v[138:139], 1, v[16:17]
	s_waitcnt vmcnt(18)
	v_pk_fma_f32 v[10:11], v[10:11], 0.5, v[188:189] op_sel_hi:[1,0,1]
	v_pk_fma_f32 v[14:15], v[14:15], 0.5, v[184:185] op_sel_hi:[1,0,1]
	v_pk_fma_f32 v[12:13], v[12:13], 0.5, v[182:183] op_sel_hi:[1,0,1]
	v_pk_fma_f32 v[8:9], v[8:9], 0.5, v[186:187] op_sel_hi:[1,0,1]
	global_store_dwordx4 v[24:25], v[12:15], off
	global_store_dwordx4 v[24:25], v[8:11], off offset:16
	v_cvt_pk_bf16_f32 v16, v12, v13
	v_mul_f32_e32 v13, v13, v13
	v_fmac_f32_e32 v13, v12, v12
	v_mul_f32_e32 v12, v15, v15
	v_cvt_pk_bf16_f32 v18, v8, v9
	v_fmac_f32_e32 v12, v14, v14
	v_mul_f32_e32 v9, v9, v9
	v_add_f32_e32 v12, v13, v12
	v_fmac_f32_e32 v9, v8, v8
	v_cvt_pk_bf16_f32 v17, v14, v15
	v_cvt_pk_bf16_f32 v19, v10, v11
	v_add_f32_e32 v8, v9, v12
	v_mul_f32_e32 v9, v11, v11
	global_store_dwordx4 v[28:29], v[16:19], off
	v_fmac_f32_e32 v9, v10, v10
	s_nop 0
	v_add_f32_e32 v16, v9, v8
	s_nop 1
	v_pk_fma_f32 v[2:3], v[2:3], 0.5, v[196:197] op_sel_hi:[1,0,1]
	v_pk_fma_f32 v[6:7], v[6:7], 0.5, v[192:193] op_sel_hi:[1,0,1]
	v_pk_fma_f32 v[4:5], v[4:5], 0.5, v[190:191] op_sel_hi:[1,0,1]
	v_pk_fma_f32 v[0:1], v[0:1], 0.5, v[194:195] op_sel_hi:[1,0,1]
	global_store_dwordx4 v[24:25], v[4:7], off offset:512
	global_store_dwordx4 v[24:25], v[0:3], off offset:528
	v_cvt_pk_bf16_f32 v8, v4, v5
	v_mul_f32_e32 v5, v5, v5
	v_fmac_f32_e32 v5, v4, v4
	v_mul_f32_e32 v4, v7, v7
	v_cvt_pk_bf16_f32 v10, v0, v1
	v_fmac_f32_e32 v4, v6, v6
	v_mul_f32_e32 v1, v1, v1
	v_add_f32_e32 v4, v5, v4
	v_fmac_f32_e32 v1, v0, v0
	v_add_f32_e32 v0, v1, v4
	v_mul_f32_e32 v1, v3, v3
	v_fmac_f32_e32 v1, v2, v2
	v_add_f32_e32 v0, v1, v0
	v_add_f32_e32 v0, v16, v0
	ds_bpermute_b32 v1, v121, v0
	v_cvt_pk_bf16_f32 v9, v6, v7
	v_cvt_pk_bf16_f32 v11, v2, v3
	global_store_dwordx4 v[28:29], v[8:11], off offset:256
	s_waitcnt lgkmcnt(0)
	v_add_f32_e32 v0, v0, v1
	ds_bpermute_b32 v1, v120, v0
	s_and_saveexec_b64 s[16:17], s[42:43]
	s_cbranch_execz .LBB0_189
	s_waitcnt lgkmcnt(0)
	v_add_f32_e32 v0, v0, v1
	v_mul_f32_e32 v0, 0x4b800000, v0
	v_trunc_f32_e32 v0, v0
	v_mul_f32_e32 v1, 0x2f800000, v0
	v_floor_f32_e32 v1, v1
	v_fmac_f32_e32 v0, 0xcf800000, v1
	v_cvt_u32_f32_e32 v0, v0
	v_cvt_u32_f32_e32 v1, v1
	global_atomic_add_x2 v[112:113], v[0:1], off offset:1408

; #define PG8_WAIT_V(n) asm volatile("s_waitcnt vmcnt(" #n ")" ::: "memory")
; #define PG8_BAR __builtin_amdgcn_s_barrier()
; template <class Epi, bool ALIGN_EPI = true>
; __device__ __forceinline__ void gemm_phase(LAS unsigned char* lds, const Gemm g, const StaticOrder& S, const Epi& E, int wave_k) {
;     ...
;     PG8_WAIT_V(0);
;     if constexpr (!ALIGN_EPI) { if (wr == 0) PG8_BAR; }
;     PG8_BAR;
; __device__ __forceinline__ void xcd_barrier_head(const XcdBarrier& b) {
;     asm volatile("s_waitcnt vmcnt(0)" ::: "memory");
;     __syncthreads();
;     if (threadIdx.x == 0) {
;         unsigned* bar = b.bar;
;         __builtin_amdgcn_s_waitcnt(0);
;         unsigned nloc = b.st[0], nx = b.st[1];
;         if (nloc == 0u) { xcd_barrier_complete(bar, b.x, nloc, nx); b.st[0] = nloc; b.st[1] = nx; }
.LBB0_192:
	v_readlane_b32 s54, v255, 0
	v_readlane_b32 s56, v255, 2
	v_readlane_b32 s52, v255, 4
	v_readlane_b32 s55, v255, 1
	v_readlane_b32 s57, v255, 3
	v_readlane_b32 s53, v255, 5
	s_barrier
.LBB0_193:
	s_waitcnt lgkmcnt(0)
	s_barrier
	s_and_saveexec_b64 s[0:1], s[88:89]
	v_readlane_b32 s34, v255, 6
	v_readlane_b32 s36, v255, 8
	v_readlane_b32 s35, v255, 7
	v_readlane_b32 s37, v255, 9
	s_cbranch_execz .LBB0_245
	v_readlane_b32 s2, v254, 50
	s_waitcnt vmcnt(0) expcnt(0) lgkmcnt(0)
	s_nop 0
	v_mov_b32_e32 v0, s2
	ds_read_b32 v2, v0
	v_readlane_b32 s2, v254, 51
	s_waitcnt lgkmcnt(0)
	v_cmp_ne_u32_e32 vcc, 0, v2
	v_mov_b32_e32 v0, s2
	ds_read_b32 v0, v0
	s_cbranch_vccnz .LBB0_209
	s_mov_b32 s18, 1
	s_branch .LBB0_197

; __device__ __forceinline__ unsigned cvtpk(float lo, float hi) { f32x2_t v = {lo, hi}; bf16x2_t b = __builtin_convertvector(v, bf16x2_t); return __builtin_bit_cast(unsigned, b); }
;     __device__ __forceinline__ void operator()(const Acc& acc, const Unit& u, int wr, int wc, int fr, int fq) const {
;         const int row0 = u.pm * BM + wr * 64 + fr, col0 = u.pn * BM + wc * 32 + 8 * fq;
; #pragma unroll
;         for (int ai = 0; ai < 2; ++ai)
; #pragma unroll
;             for (int m = 0; m < 4; ++m) { const int row = row0 + ai * HALF + m * 16; float* rp = X + (size_t)row * DM + col0; const float* ip = Xin + (size_t)row * DM + col0; bf16_t* bp = XB + (size_t)row * DM + col0; float part = 0.f;
; #pragma unroll
;                 for (int bj = 0; bj < 2; ++bj) { f32x4* p = (f32x4*)(rp + bj * HALF); const f32x4* q = (const f32x4*)(ip + bj * HALF); f32x4 a = q[0], b = q[1]; a += acc[ai][bj][m][0] * scale; b += acc[ai][bj][m][1] * scale; p[0] = a; p[1] = b;
;                     *(u32x4*)(bp + bj * HALF) = (u32x4){cvtpk(a[0], a[1]), cvtpk(a[2], a[3]), cvtpk(b[0], b[1]), cvtpk(b[2], b[3])};
;                     part += (a[0] * a[0] + a[1] * a[1]) + (a[2] * a[2] + a[3] * a[3]) + (b[0] * b[0] + b[1] * b[1]) + (b[2] * b[2] + b[3] * b[3]); }
;                 part += __shfl_xor(part, 16); part += __shfl_xor(part, 32);
;                 if (fq == 0) __hip_atomic_fetch_add(SS + row, (u64)(part * SSF), __ATOMIC_RELAXED, __HIP_MEMORY_SCOPE_AGENT); }
.LBB0_1060:
	v_lshl_add_u32 v140, s46, 8, v142
	v_ashrrev_i32_e32 v141, 31, v140
	v_lshl_or_b32 v138, s52, 8, v144
	v_lshlrev_b64 v[146:147], 12, v[140:141]
	v_ashrrev_i32_e32 v139, 31, v138
	v_lshl_add_u64 v[146:147], s[48:49], 0, v[146:147]
	v_lshl_add_u64 v[158:159], v[138:139], 2, v[146:147]
	v_mov_b64_e32 v[218:219], v[158:159]
	global_load_dwordx4 v[166:169], v[218:219], off
	global_load_dwordx4 v[170:173], v[218:219], off offset:16
	global_load_dwordx4 v[174:177], v[218:219], off offset:512
	global_load_dwordx4 v[178:181], v[218:219], off offset:528
	v_mov_b32_e32 v220, 0x10000
	v_mov_b32_e32 v221, 0
	v_lshl_add_u64 v[220:221], v[220:221], 0, v[218:219]
	global_load_dwordx4 v[182:185], v[220:221], off
	global_load_dwordx4 v[186:189], v[220:221], off offset:16
	global_load_dwordx4 v[190:193], v[220:221], off offset:512
	global_load_dwordx4 v[194:197], v[220:221], off offset:528
	v_mov_b32_e32 v220, 0x20000
	v_mov_b32_e32 v221, 0
	v_lshl_add_u64 v[220:221], v[220:221], 0, v[218:219]
	global_load_dwordx4 v[198:201], v[220:221], off
	global_load_dwordx4 v[202:205], v[220:221], off offset:16
	global_load_dwordx4 v[206:209], v[220:221], off offset:512
	global_load_dwordx4 v[210:213], v[220:221], off offset:528
	v_lshlrev_b64 v[154:155], 11, v[140:141]
	v_lshl_add_u64 v[154:155], s[14:15], 0, v[154:155]
	v_lshl_add_u64 v[162:163], v[138:139], 1, v[154:155]
	s_waitcnt vmcnt(8)
	v_pk_add_f32 v[126:127], v[126:127], v[168:169]
	v_pk_add_f32 v[124:125], v[124:125], v[166:167]
	v_pk_add_f32 v[148:149], v[122:123], v[172:173]
	v_pk_add_f32 v[146:147], v[120:121], v[170:171]
	v_cvt_pk_bf16_f32 v120, v124, v125
	v_cvt_pk_bf16_f32 v121, v126, v127
	v_cvt_pk_bf16_f32 v122, v146, v147
	v_cvt_pk_bf16_f32 v123, v148, v149
	global_store_dwordx4 v[158:159], v[124:127], off
	global_store_dwordx4 v[158:159], v[146:149], off offset:16
	global_store_dwordx4 v[162:163], v[120:123], off
	s_nop 1
	v_and_b32_e32 v121, 64, v229
	v_xor_b32_e32 v120, 16, v229
	v_add_u32_e32 v121, 64, v121
	v_xor_b32_e32 v122, 32, v229
	v_cmp_lt_i32_e32 vcc, v120, v121
	v_mul_f32_e32 v123, v127, v127
	v_fmac_f32_e32 v123, v126, v126
	v_cndmask_b32_e32 v120, v229, v120, vcc
	v_cmp_lt_i32_e32 vcc, v122, v121
	v_lshlrev_b32_e32 v121, 2, v120
	v_mul_f32_e32 v127, v149, v149
	v_cndmask_b32_e32 v122, v229, v122, vcc
	v_lshlrev_b32_e32 v120, 2, v122
	v_mul_f32_e32 v122, v125, v125
	v_mul_f32_e32 v125, v147, v147
	v_fmac_f32_e32 v122, v124, v124
	v_fmac_f32_e32 v125, v146, v146
	v_add_f32_e32 v122, v122, v123
	v_fmac_f32_e32 v127, v148, v148
	v_add_f32_e32 v122, v125, v122
	v_add_f32_e32 v126, v127, v122
	v_pk_add_f32 v[118:119], v[118:119], v[176:177]
	v_pk_add_f32 v[116:117], v[116:117], v[174:175]
	v_pk_add_f32 v[122:123], v[112:113], v[178:179]
	v_mul_f32_e32 v112, v117, v117
	v_mul_f32_e32 v113, v119, v119
	v_pk_add_f32 v[124:125], v[114:115], v[180:181]
	v_mov_b32_e32 v220, 0x30000
	v_mov_b32_e32 v221, 0
	v_lshl_add_u64 v[220:221], v[220:221], 0, v[218:219]
	global_load_dwordx4 v[166:169], v[220:221], off
	global_load_dwordx4 v[170:173], v[220:221], off offset:16
	global_load_dwordx4 v[174:177], v[220:221], off offset:512
	global_load_dwordx4 v[178:181], v[220:221], off offset:528
	v_mul_f32_e32 v114, v123, v123
	v_fmac_f32_e32 v112, v116, v116
	v_fmac_f32_e32 v113, v118, v118
	v_mul_f32_e32 v115, v125, v125
	v_fmac_f32_e32 v114, v122, v122
	v_add_f32_e32 v112, v112, v113
	v_add_f32_e32 v112, v114, v112
	v_fmac_f32_e32 v115, v124, v124
	v_add_f32_e32 v112, v115, v112
	v_add_f32_e32 v112, v126, v112
	ds_bpermute_b32 v113, v121, v112
	global_store_dwordx4 v[158:159], v[116:119], off offset:512
	global_store_dwordx4 v[158:159], v[122:125], off offset:528
	s_waitcnt lgkmcnt(0)
	v_add_f32_e32 v114, v112, v113
	ds_bpermute_b32 v115, v120, v114
	v_cvt_pk_bf16_f32 v116, v116, v117
	v_cvt_pk_bf16_f32 v117, v118, v119
	v_cvt_pk_bf16_f32 v118, v122, v123
	v_cvt_pk_bf16_f32 v119, v124, v125
	v_lshl_add_u64 v[112:113], v[140:141], 3, s[18:19]
	global_store_dwordx4 v[162:163], v[116:119], off offset:256
	s_and_saveexec_b64 s[16:17], s[42:43]
	s_cbranch_execz .LBB0_1062
	s_waitcnt lgkmcnt(0)
	v_add_f32_e32 v114, v114, v115
	v_mul_f32_e32 v114, 0x4b800000, v114
	v_trunc_f32_e32 v114, v114
	v_mul_f32_e32 v115, 0x2f800000, v114
	v_floor_f32_e32 v115, v115
	v_fmac_f32_e32 v114, 0xcf800000, v115
	v_cvt_u32_f32_e32 v114, v114
	v_cvt_u32_f32_e32 v115, v115
	global_atomic_add_x2 v[112:113], v[114:115], off
; __device__ __forceinline__ unsigned cvtpk(float lo, float hi) { f32x2_t v = {lo, hi}; bf16x2_t b = __builtin_convertvector(v, bf16x2_t); return __builtin_bit_cast(unsigned, b); }
;     __device__ __forceinline__ void operator()(const Acc& acc, const Unit& u, int wr, int wc, int fr, int fq) const {
;         const int row0 = u.pm * BM + wr * 64 + fr, col0 = u.pn * BM + wc * 32 + 8 * fq;
; #pragma unroll
;         for (int ai = 0; ai < 2; ++ai)
; #pragma unroll
;             for (int m = 0; m < 4; ++m) { const int row = row0 + ai * HALF + m * 16; float* rp = X + (size_t)row * DM + col0; const float* ip = Xin + (size_t)row * DM + col0; bf16_t* bp = XB + (size_t)row * DM + col0; float part = 0.f;
; #pragma unroll
;                 for (int bj = 0; bj < 2; ++bj) { f32x4* p = (f32x4*)(rp + bj * HALF); const f32x4* q = (const f32x4*)(ip + bj * HALF); f32x4 a = q[0], b = q[1]; a += acc[ai][bj][m][0] * scale; b += acc[ai][bj][m][1] * scale; p[0] = a; p[1] = b;
;                     *(u32x4*)(bp + bj * HALF) = (u32x4){cvtpk(a[0], a[1]), cvtpk(a[2], a[3]), cvtpk(b[0], b[1]), cvtpk(b[2], b[3])};
;                     part += (a[0] * a[0] + a[1] * a[1]) + (a[2] * a[2] + a[3] * a[3]) + (b[0] * b[0] + b[1] * b[1]) + (b[2] * b[2] + b[3] * b[3]); }
;                 part += __shfl_xor(part, 16); part += __shfl_xor(part, 32);
;                 if (fq == 0) __hip_atomic_fetch_add(SS + row, (u64)(part * SSF), __ATOMIC_RELAXED, __HIP_MEMORY_SCOPE_AGENT); }
.LBB0_1062:
	s_or_b64 exec, exec, s[16:17]
	v_or_b32_e32 v118, 16, v140
	v_ashrrev_i32_e32 v119, 31, v118
	s_waitcnt lgkmcnt(0)
	v_lshlrev_b64 v[114:115], 12, v[118:119]
	v_lshl_add_u64 v[114:115], s[48:49], 0, v[114:115]
	v_lshl_add_u64 v[126:127], v[138:139], 2, v[114:115]
	v_lshlrev_b64 v[118:119], 11, v[118:119]
	v_lshl_add_u64 v[118:119], s[14:15], 0, v[118:119]
	v_lshl_add_u64 v[118:119], v[138:139], 1, v[118:119]
	s_waitcnt vmcnt(15)
	v_pk_add_f32 v[110:111], v[110:111], v[184:185]
	v_pk_add_f32 v[108:109], v[108:109], v[182:183]
	v_pk_add_f32 v[106:107], v[106:107], v[188:189]
	v_pk_add_f32 v[104:105], v[104:105], v[186:187]
	v_cvt_pk_bf16_f32 v114, v108, v109
	v_cvt_pk_bf16_f32 v115, v110, v111
	v_cvt_pk_bf16_f32 v116, v104, v105
	v_cvt_pk_bf16_f32 v117, v106, v107
	global_store_dwordx4 v[126:127], v[108:111], off
	global_store_dwordx4 v[126:127], v[104:107], off offset:16
	global_store_dwordx4 v[118:119], v[114:117], off
	s_nop 1
	v_mul_f32_e32 v109, v109, v109
	v_mul_f32_e32 v111, v111, v111
	v_mul_f32_e32 v105, v105, v105
	v_fmac_f32_e32 v109, v108, v108
	v_fmac_f32_e32 v111, v110, v110
	v_mul_f32_e32 v107, v107, v107
	v_fmac_f32_e32 v105, v104, v104
	v_add_f32_e32 v104, v109, v111
	v_fmac_f32_e32 v107, v106, v106
	v_add_f32_e32 v104, v105, v104
	v_add_f32_e32 v108, v107, v104
	v_pk_add_f32 v[102:103], v[102:103], v[192:193]
	v_pk_add_f32 v[100:101], v[100:101], v[190:191]
	v_pk_add_f32 v[104:105], v[96:97], v[194:195]
	v_mul_f32_e32 v96, v101, v101
	v_mul_f32_e32 v97, v103, v103
	v_pk_add_f32 v[106:107], v[98:99], v[196:197]
	v_mov_b32_e32 v220, 0x80000
	v_mov_b32_e32 v221, 0
	v_lshl_add_u64 v[220:221], v[220:221], 0, v[218:219]
	global_load_dwordx4 v[182:185], v[220:221], off
	global_load_dwordx4 v[186:189], v[220:221], off offset:16
	global_load_dwordx4 v[190:193], v[220:221], off offset:512
	global_load_dwordx4 v[194:197], v[220:221], off offset:528
	v_mul_f32_e32 v98, v105, v105
	v_fmac_f32_e32 v96, v100, v100
	v_fmac_f32_e32 v97, v102, v102
	v_mul_f32_e32 v99, v107, v107
	v_fmac_f32_e32 v98, v104, v104
	v_add_f32_e32 v96, v96, v97
	v_add_f32_e32 v96, v98, v96
	v_fmac_f32_e32 v99, v106, v106
	v_add_f32_e32 v96, v99, v96
	v_add_f32_e32 v96, v108, v96
	ds_bpermute_b32 v97, v121, v96
	global_store_dwordx4 v[126:127], v[100:103], off offset:512
	global_store_dwordx4 v[126:127], v[104:107], off offset:528
	v_cvt_pk_bf16_f32 v98, v100, v101
	v_cvt_pk_bf16_f32 v99, v102, v103
	v_cvt_pk_bf16_f32 v100, v104, v105
	s_waitcnt lgkmcnt(0)
	v_add_f32_e32 v96, v96, v97
	ds_bpermute_b32 v97, v120, v96
	v_cvt_pk_bf16_f32 v101, v106, v107
	global_store_dwordx4 v[118:119], v[98:101], off offset:256
	s_and_saveexec_b64 s[16:17], s[42:43]
	s_cbranch_execz .LBB0_1064
	s_waitcnt lgkmcnt(0)
	v_add_f32_e32 v96, v96, v97
	v_mul_f32_e32 v96, 0x4b800000, v96
	v_trunc_f32_e32 v96, v96
	v_mul_f32_e32 v97, 0x2f800000, v96
	v_floor_f32_e32 v97, v97
	v_fmac_f32_e32 v96, 0xcf800000, v97
	v_cvt_u32_f32_e32 v96, v96
	v_cvt_u32_f32_e32 v97, v97
	global_atomic_add_x2 v[112:113], v[96:97], off offset:128
.LBB0_1064:
	s_or_b64 exec, exec, s[16:17]
	v_or_b32_e32 v104, 32, v140
	v_ashrrev_i32_e32 v105, 31, v104
	s_waitcnt lgkmcnt(0)
	v_lshlrev_b64 v[96:97], 12, v[104:105]
	v_lshl_add_u64 v[96:97], s[48:49], 0, v[96:97]
	v_lshl_add_u64 v[106:107], v[138:139], 2, v[96:97]
	v_lshlrev_b64 v[104:105], 11, v[104:105]
	v_lshl_add_u64 v[104:105], s[14:15], 0, v[104:105]
	v_lshl_add_u64 v[104:105], v[138:139], 1, v[104:105]
	s_waitcnt vmcnt(22)
	v_pk_add_f32 v[94:95], v[94:95], v[200:201]
	v_pk_add_f32 v[92:93], v[92:93], v[198:199]
	v_pk_add_f32 v[90:91], v[90:91], v[204:205]
	v_pk_add_f32 v[88:89], v[88:89], v[202:203]
	v_cvt_pk_bf16_f32 v96, v92, v93
	v_cvt_pk_bf16_f32 v97, v94, v95
	v_cvt_pk_bf16_f32 v98, v88, v89
	v_cvt_pk_bf16_f32 v99, v90, v91
	global_store_dwordx4 v[106:107], v[92:95], off
	global_store_dwordx4 v[106:107], v[88:91], off offset:16
	global_store_dwordx4 v[104:105], v[96:99], off
	s_nop 1
	v_mul_f32_e32 v93, v93, v93
	v_mul_f32_e32 v95, v95, v95
	v_mul_f32_e32 v89, v89, v89
	v_fmac_f32_e32 v93, v92, v92
	v_fmac_f32_e32 v95, v94, v94
	v_mul_f32_e32 v91, v91, v91
	v_fmac_f32_e32 v89, v88, v88
	v_add_f32_e32 v88, v93, v95
	v_fmac_f32_e32 v91, v90, v90
	v_add_f32_e32 v88, v89, v88
	v_add_f32_e32 v92, v91, v88
	v_pk_add_f32 v[86:87], v[86:87], v[208:209]
	v_pk_add_f32 v[84:85], v[84:85], v[206:207]
	v_pk_add_f32 v[88:89], v[80:81], v[210:211]
	v_mul_f32_e32 v80, v85, v85
	v_mul_f32_e32 v81, v87, v87
	v_pk_add_f32 v[90:91], v[82:83], v[212:213]
	v_mov_b32_e32 v220, 0x90000
	v_mov_b32_e32 v221, 0
	v_lshl_add_u64 v[220:221], v[220:221], 0, v[218:219]
	global_load_dwordx4 v[198:201], v[220:221], off
	global_load_dwordx4 v[202:205], v[220:221], off offset:16
	global_load_dwordx4 v[206:209], v[220:221], off offset:512
	global_load_dwordx4 v[210:213], v[220:221], off offset:528
	v_mul_f32_e32 v82, v89, v89
	v_fmac_f32_e32 v80, v84, v84
	v_fmac_f32_e32 v81, v86, v86
	v_mul_f32_e32 v83, v91, v91
	v_fmac_f32_e32 v82, v88, v88
	v_add_f32_e32 v80, v80, v81
	v_add_f32_e32 v80, v82, v80
	v_fmac_f32_e32 v83, v90, v90
	v_add_f32_e32 v80, v83, v80
	v_add_f32_e32 v80, v92, v80
	ds_bpermute_b32 v81, v121, v80
	global_store_dwordx4 v[106:107], v[84:87], off offset:512
	global_store_dwordx4 v[106:107], v[88:91], off offset:528
	v_cvt_pk_bf16_f32 v82, v84, v85
	v_cvt_pk_bf16_f32 v83, v86, v87
	v_cvt_pk_bf16_f32 v84, v88, v89
	s_waitcnt lgkmcnt(0)
	v_add_f32_e32 v80, v80, v81
	ds_bpermute_b32 v81, v120, v80
	v_cvt_pk_bf16_f32 v85, v90, v91
	global_store_dwordx4 v[104:105], v[82:85], off offset:256
	s_and_saveexec_b64 s[16:17], s[42:43]
	s_cbranch_execz .LBB0_1066
	s_waitcnt lgkmcnt(0)
	v_add_f32_e32 v80, v80, v81
	v_mul_f32_e32 v80, 0x4b800000, v80
	v_trunc_f32_e32 v80, v80
	v_mul_f32_e32 v81, 0x2f800000, v80
	v_floor_f32_e32 v81, v81
	v_fmac_f32_e32 v80, 0xcf800000, v81
	v_cvt_u32_f32_e32 v80, v80
	v_cvt_u32_f32_e32 v81, v81
	global_atomic_add_x2 v[112:113], v[80:81], off offset:256
; __device__ __forceinline__ unsigned cvtpk(float lo, float hi) { f32x2_t v = {lo, hi}; bf16x2_t b = __builtin_convertvector(v, bf16x2_t); return __builtin_bit_cast(unsigned, b); }
;     __device__ __forceinline__ void operator()(const Acc& acc, const Unit& u, int wr, int wc, int fr, int fq) const {
;         const int row0 = u.pm * BM + wr * 64 + fr, col0 = u.pn * BM + wc * 32 + 8 * fq;
; #pragma unroll
;         for (int ai = 0; ai < 2; ++ai)
; #pragma unroll
;             for (int m = 0; m < 4; ++m) { const int row = row0 + ai * HALF + m * 16; float* rp = X + (size_t)row * DM + col0; const float* ip = Xin + (size_t)row * DM + col0; bf16_t* bp = XB + (size_t)row * DM + col0; float part = 0.f;
; #pragma unroll
;                 for (int bj = 0; bj < 2; ++bj) { f32x4* p = (f32x4*)(rp + bj * HALF); const f32x4* q = (const f32x4*)(ip + bj * HALF); f32x4 a = q[0], b = q[1]; a += acc[ai][bj][m][0] * scale; b += acc[ai][bj][m][1] * scale; p[0] = a; p[1] = b;
;                     *(u32x4*)(bp + bj * HALF) = (u32x4){cvtpk(a[0], a[1]), cvtpk(a[2], a[3]), cvtpk(b[0], b[1]), cvtpk(b[2], b[3])};
;                     part += (a[0] * a[0] + a[1] * a[1]) + (a[2] * a[2] + a[3] * a[3]) + (b[0] * b[0] + b[1] * b[1]) + (b[2] * b[2] + b[3] * b[3]); }
;                 part += __shfl_xor(part, 16); part += __shfl_xor(part, 32);
;                 if (fq == 0) __hip_atomic_fetch_add(SS + row, (u64)(part * SSF), __ATOMIC_RELAXED, __HIP_MEMORY_SCOPE_AGENT); }
.LBB0_1066:
	s_or_b64 exec, exec, s[16:17]
	v_or_b32_e32 v88, 48, v140
	v_ashrrev_i32_e32 v89, 31, v88
	s_waitcnt lgkmcnt(0)
	v_lshlrev_b64 v[80:81], 12, v[88:89]
	v_lshl_add_u64 v[80:81], s[48:49], 0, v[80:81]
	v_lshl_add_u64 v[90:91], v[138:139], 2, v[80:81]
	v_lshlrev_b64 v[88:89], 11, v[88:89]
	v_lshl_add_u64 v[88:89], s[14:15], 0, v[88:89]
	v_lshl_add_u64 v[88:89], v[138:139], 1, v[88:89]
	s_waitcnt vmcnt(26)
	v_pk_add_f32 v[78:79], v[78:79], v[168:169]
	v_pk_add_f32 v[76:77], v[76:77], v[166:167]
	v_pk_add_f32 v[74:75], v[74:75], v[172:173]
	v_pk_add_f32 v[72:73], v[72:73], v[170:171]
	v_cvt_pk_bf16_f32 v80, v76, v77
	v_cvt_pk_bf16_f32 v81, v78, v79
	v_cvt_pk_bf16_f32 v82, v72, v73
	v_cvt_pk_bf16_f32 v83, v74, v75
	global_store_dwordx4 v[90:91], v[76:79], off
	global_store_dwordx4 v[90:91], v[72:75], off offset:16
	global_store_dwordx4 v[88:89], v[80:83], off
	s_nop 1
	v_mul_f32_e32 v77, v77, v77
	v_mul_f32_e32 v79, v79, v79
	v_mul_f32_e32 v73, v73, v73
	v_fmac_f32_e32 v77, v76, v76
	v_fmac_f32_e32 v79, v78, v78
	v_mul_f32_e32 v75, v75, v75
	v_fmac_f32_e32 v73, v72, v72
	v_add_f32_e32 v72, v77, v79
	v_fmac_f32_e32 v75, v74, v74
	v_add_f32_e32 v72, v73, v72
	v_add_f32_e32 v76, v75, v72
	v_pk_add_f32 v[70:71], v[70:71], v[176:177]
	v_pk_add_f32 v[68:69], v[68:69], v[174:175]
	v_pk_add_f32 v[72:73], v[64:65], v[178:179]
	v_mul_f32_e32 v64, v69, v69
	v_mul_f32_e32 v65, v71, v71
	v_pk_add_f32 v[74:75], v[66:67], v[180:181]
	v_mov_b32_e32 v220, 0xa0000
	v_mov_b32_e32 v221, 0
	v_lshl_add_u64 v[220:221], v[220:221], 0, v[218:219]
	global_load_dwordx4 v[166:169], v[220:221], off
	global_load_dwordx4 v[170:173], v[220:221], off offset:16
	global_load_dwordx4 v[174:177], v[220:221], off offset:512
	global_load_dwordx4 v[178:181], v[220:221], off offset:528
	v_mul_f32_e32 v66, v73, v73
	v_fmac_f32_e32 v64, v68, v68
	v_fmac_f32_e32 v65, v70, v70
	v_mul_f32_e32 v67, v75, v75
	v_fmac_f32_e32 v66, v72, v72
	v_add_f32_e32 v64, v64, v65
	v_add_f32_e32 v64, v66, v64
	v_fmac_f32_e32 v67, v74, v74
	v_add_f32_e32 v64, v67, v64
	v_add_f32_e32 v64, v76, v64
	ds_bpermute_b32 v65, v121, v64
	global_store_dwordx4 v[90:91], v[68:71], off offset:512
	global_store_dwordx4 v[90:91], v[72:75], off offset:528
	v_cvt_pk_bf16_f32 v66, v68, v69
	v_cvt_pk_bf16_f32 v67, v70, v71
	v_cvt_pk_bf16_f32 v68, v72, v73
	s_waitcnt lgkmcnt(0)
	v_add_f32_e32 v64, v64, v65
	ds_bpermute_b32 v65, v120, v64
	v_cvt_pk_bf16_f32 v69, v74, v75
	global_store_dwordx4 v[88:89], v[66:69], off offset:256
	s_and_saveexec_b64 s[16:17], s[42:43]
	s_cbranch_execz .LBB0_1068
	s_waitcnt lgkmcnt(0)
	v_add_f32_e32 v64, v64, v65
	v_mul_f32_e32 v64, 0x4b800000, v64
	v_trunc_f32_e32 v64, v64
	v_mul_f32_e32 v65, 0x2f800000, v64
	v_floor_f32_e32 v65, v65
	v_fmac_f32_e32 v64, 0xcf800000, v65
	v_cvt_u32_f32_e32 v64, v64
	v_cvt_u32_f32_e32 v65, v65
	global_atomic_add_x2 v[112:113], v[64:65], off offset:384
.LBB0_1068:
	s_or_b64 exec, exec, s[16:17]
	v_add_u32_e32 v72, 0x80, v140
	v_ashrrev_i32_e32 v73, 31, v72
	s_waitcnt lgkmcnt(0)
	v_lshlrev_b64 v[64:65], 12, v[72:73]
	v_lshl_add_u64 v[64:65], s[48:49], 0, v[64:65]
	v_lshl_add_u64 v[74:75], v[138:139], 2, v[64:65]
	v_lshlrev_b64 v[72:73], 11, v[72:73]
	v_lshl_add_u64 v[72:73], s[14:15], 0, v[72:73]
	v_lshl_add_u64 v[72:73], v[138:139], 1, v[72:73]
	s_waitcnt vmcnt(26)
	v_pk_add_f32 v[62:63], v[62:63], v[184:185]
	v_pk_add_f32 v[60:61], v[60:61], v[182:183]
	v_pk_add_f32 v[58:59], v[58:59], v[188:189]
	v_pk_add_f32 v[56:57], v[56:57], v[186:187]
	v_cvt_pk_bf16_f32 v64, v60, v61
	v_cvt_pk_bf16_f32 v65, v62, v63
	v_cvt_pk_bf16_f32 v66, v56, v57
	v_cvt_pk_bf16_f32 v67, v58, v59
	global_store_dwordx4 v[74:75], v[60:63], off
	global_store_dwordx4 v[74:75], v[56:59], off offset:16
	global_store_dwordx4 v[72:73], v[64:67], off
	s_nop 1
	v_mul_f32_e32 v61, v61, v61
	v_mul_f32_e32 v63, v63, v63
	v_mul_f32_e32 v57, v57, v57
	v_fmac_f32_e32 v61, v60, v60
	v_fmac_f32_e32 v63, v62, v62
	v_mul_f32_e32 v59, v59, v59
	v_fmac_f32_e32 v57, v56, v56
	v_add_f32_e32 v56, v61, v63
	v_fmac_f32_e32 v59, v58, v58
	v_add_f32_e32 v56, v57, v56
	v_add_f32_e32 v60, v59, v56
	v_pk_add_f32 v[54:55], v[54:55], v[192:193]
	v_pk_add_f32 v[52:53], v[52:53], v[190:191]
	v_pk_add_f32 v[56:57], v[48:49], v[194:195]
	v_mul_f32_e32 v48, v53, v53
	v_mul_f32_e32 v49, v55, v55
	v_pk_add_f32 v[58:59], v[50:51], v[196:197]
	v_mov_b32_e32 v220, 0xb0000
	v_mov_b32_e32 v221, 0
	v_lshl_add_u64 v[220:221], v[220:221], 0, v[218:219]
	global_load_dwordx4 v[182:185], v[220:221], off
	global_load_dwordx4 v[186:189], v[220:221], off offset:16
	global_load_dwordx4 v[190:193], v[220:221], off offset:512
	global_load_dwordx4 v[194:197], v[220:221], off offset:528
	v_mul_f32_e32 v50, v57, v57
	v_fmac_f32_e32 v48, v52, v52
	v_fmac_f32_e32 v49, v54, v54
	v_mul_f32_e32 v51, v59, v59
	v_fmac_f32_e32 v50, v56, v56
	v_add_f32_e32 v48, v48, v49
	v_add_f32_e32 v48, v50, v48
	v_fmac_f32_e32 v51, v58, v58
	v_add_f32_e32 v48, v51, v48
	v_add_f32_e32 v48, v60, v48
	ds_bpermute_b32 v49, v121, v48
	global_store_dwordx4 v[74:75], v[52:55], off offset:512
	global_store_dwordx4 v[74:75], v[56:59], off offset:528
	v_cvt_pk_bf16_f32 v50, v52, v53
	v_cvt_pk_bf16_f32 v51, v54, v55
	v_cvt_pk_bf16_f32 v52, v56, v57
	s_waitcnt lgkmcnt(0)
	v_add_f32_e32 v48, v48, v49
	ds_bpermute_b32 v49, v120, v48
	v_cvt_pk_bf16_f32 v53, v58, v59
	global_store_dwordx4 v[72:73], v[50:53], off offset:256
	s_and_saveexec_b64 s[16:17], s[42:43]
	s_cbranch_execz .LBB0_1070
	s_waitcnt lgkmcnt(0)
	v_add_f32_e32 v48, v48, v49
	v_mul_f32_e32 v48, 0x4b800000, v48
	v_trunc_f32_e32 v48, v48
	v_mul_f32_e32 v49, 0x2f800000, v48
	v_floor_f32_e32 v49, v49
	v_fmac_f32_e32 v48, 0xcf800000, v49
	v_cvt_u32_f32_e32 v48, v48
	v_cvt_u32_f32_e32 v49, v49
	global_atomic_add_x2 v[112:113], v[48:49], off offset:1024
; __device__ __forceinline__ unsigned cvtpk(float lo, float hi) { f32x2_t v = {lo, hi}; bf16x2_t b = __builtin_convertvector(v, bf16x2_t); return __builtin_bit_cast(unsigned, b); }
;     __device__ __forceinline__ void operator()(const Acc& acc, const Unit& u, int wr, int wc, int fr, int fq) const {
;         const int row0 = u.pm * BM + wr * 64 + fr, col0 = u.pn * BM + wc * 32 + 8 * fq;
; #pragma unroll
;         for (int ai = 0; ai < 2; ++ai)
; #pragma unroll
;             for (int m = 0; m < 4; ++m) { const int row = row0 + ai * HALF + m * 16; float* rp = X + (size_t)row * DM + col0; const float* ip = Xin + (size_t)row * DM + col0; bf16_t* bp = XB + (size_t)row * DM + col0; float part = 0.f;
; #pragma unroll
;                 for (int bj = 0; bj < 2; ++bj) { f32x4* p = (f32x4*)(rp + bj * HALF); const f32x4* q = (const f32x4*)(ip + bj * HALF); f32x4 a = q[0], b = q[1]; a += acc[ai][bj][m][0] * scale; b += acc[ai][bj][m][1] * scale; p[0] = a; p[1] = b;
;                     *(u32x4*)(bp + bj * HALF) = (u32x4){cvtpk(a[0], a[1]), cvtpk(a[2], a[3]), cvtpk(b[0], b[1]), cvtpk(b[2], b[3])};
;                     part += (a[0] * a[0] + a[1] * a[1]) + (a[2] * a[2] + a[3] * a[3]) + (b[0] * b[0] + b[1] * b[1]) + (b[2] * b[2] + b[3] * b[3]); }
;                 part += __shfl_xor(part, 16); part += __shfl_xor(part, 32);
;                 if (fq == 0) __hip_atomic_fetch_add(SS + row, (u64)(part * SSF), __ATOMIC_RELAXED, __HIP_MEMORY_SCOPE_AGENT); }
.LBB0_1070:
	s_or_b64 exec, exec, s[16:17]
	v_add_u32_e32 v56, 0x90, v140
	v_ashrrev_i32_e32 v57, 31, v56
	s_waitcnt lgkmcnt(0)
	v_lshlrev_b64 v[48:49], 12, v[56:57]
	v_lshl_add_u64 v[48:49], s[48:49], 0, v[48:49]
	v_lshl_add_u64 v[58:59], v[138:139], 2, v[48:49]
	v_lshlrev_b64 v[56:57], 11, v[56:57]
	v_lshl_add_u64 v[56:57], s[14:15], 0, v[56:57]
	v_lshl_add_u64 v[56:57], v[138:139], 1, v[56:57]
	s_waitcnt vmcnt(26)
	v_pk_add_f32 v[46:47], v[46:47], v[200:201]
	v_pk_add_f32 v[44:45], v[44:45], v[198:199]
	v_pk_add_f32 v[42:43], v[42:43], v[204:205]
	v_pk_add_f32 v[40:41], v[40:41], v[202:203]
	v_cvt_pk_bf16_f32 v48, v44, v45
	v_cvt_pk_bf16_f32 v49, v46, v47
	v_cvt_pk_bf16_f32 v50, v40, v41
	v_cvt_pk_bf16_f32 v51, v42, v43
	global_store_dwordx4 v[58:59], v[44:47], off
	global_store_dwordx4 v[58:59], v[40:43], off offset:16
	global_store_dwordx4 v[56:57], v[48:51], off
	s_nop 1
	v_mul_f32_e32 v45, v45, v45
	v_mul_f32_e32 v47, v47, v47
	v_mul_f32_e32 v41, v41, v41
	v_fmac_f32_e32 v45, v44, v44
	v_fmac_f32_e32 v47, v46, v46
	v_mul_f32_e32 v43, v43, v43
	v_fmac_f32_e32 v41, v40, v40
	v_add_f32_e32 v40, v45, v47
	v_fmac_f32_e32 v43, v42, v42
	v_add_f32_e32 v40, v41, v40
	v_add_f32_e32 v44, v43, v40
	v_pk_add_f32 v[38:39], v[38:39], v[208:209]
	v_pk_add_f32 v[36:37], v[36:37], v[206:207]
	v_pk_add_f32 v[40:41], v[32:33], v[210:211]
	v_mul_f32_e32 v32, v37, v37
	v_mul_f32_e32 v33, v39, v39
	v_pk_add_f32 v[42:43], v[34:35], v[212:213]
	v_mul_f32_e32 v34, v41, v41
	v_fmac_f32_e32 v32, v36, v36
	v_fmac_f32_e32 v33, v38, v38
	v_mul_f32_e32 v35, v43, v43
	v_fmac_f32_e32 v34, v40, v40
	v_add_f32_e32 v32, v32, v33
	v_add_f32_e32 v32, v34, v32
	v_fmac_f32_e32 v35, v42, v42
	v_add_f32_e32 v32, v35, v32
	v_add_f32_e32 v32, v44, v32
	ds_bpermute_b32 v33, v121, v32
	global_store_dwordx4 v[58:59], v[36:39], off offset:512
	global_store_dwordx4 v[58:59], v[40:43], off offset:528
	v_cvt_pk_bf16_f32 v34, v36, v37
	v_cvt_pk_bf16_f32 v35, v38, v39
	v_cvt_pk_bf16_f32 v36, v40, v41
	s_waitcnt lgkmcnt(0)
	v_add_f32_e32 v32, v32, v33
	ds_bpermute_b32 v33, v120, v32
	v_cvt_pk_bf16_f32 v37, v42, v43
	global_store_dwordx4 v[56:57], v[34:37], off offset:256
	s_and_saveexec_b64 s[16:17], s[42:43]
	s_cbranch_execz .LBB0_1072
	s_waitcnt lgkmcnt(0)
	v_add_f32_e32 v32, v32, v33
	v_mul_f32_e32 v32, 0x4b800000, v32
	v_trunc_f32_e32 v32, v32
	v_mul_f32_e32 v33, 0x2f800000, v32
	v_floor_f32_e32 v33, v33
	v_fmac_f32_e32 v32, 0xcf800000, v33
	v_cvt_u32_f32_e32 v32, v32
	v_cvt_u32_f32_e32 v33, v33
	global_atomic_add_x2 v[112:113], v[32:33], off offset:1152
; __device__ __forceinline__ unsigned cvtpk(float lo, float hi) { f32x2_t v = {lo, hi}; bf16x2_t b = __builtin_convertvector(v, bf16x2_t); return __builtin_bit_cast(unsigned, b); }
;     __device__ __forceinline__ void operator()(const Acc& acc, const Unit& u, int wr, int wc, int fr, int fq) const {
;         const int row0 = u.pm * BM + wr * 64 + fr, col0 = u.pn * BM + wc * 32 + 8 * fq;
; #pragma unroll
;         for (int ai = 0; ai < 2; ++ai)
; #pragma unroll
;             for (int m = 0; m < 4; ++m) { const int row = row0 + ai * HALF + m * 16; float* rp = X + (size_t)row * DM + col0; const float* ip = Xin + (size_t)row * DM + col0; bf16_t* bp = XB + (size_t)row * DM + col0; float part = 0.f;
; #pragma unroll
;                 for (int bj = 0; bj < 2; ++bj) { f32x4* p = (f32x4*)(rp + bj * HALF); const f32x4* q = (const f32x4*)(ip + bj * HALF); f32x4 a = q[0], b = q[1]; a += acc[ai][bj][m][0] * scale; b += acc[ai][bj][m][1] * scale; p[0] = a; p[1] = b;
;                     *(u32x4*)(bp + bj * HALF) = (u32x4){cvtpk(a[0], a[1]), cvtpk(a[2], a[3]), cvtpk(b[0], b[1]), cvtpk(b[2], b[3])};
;                     part += (a[0] * a[0] + a[1] * a[1]) + (a[2] * a[2] + a[3] * a[3]) + (b[0] * b[0] + b[1] * b[1]) + (b[2] * b[2] + b[3] * b[3]); }
;                 part += __shfl_xor(part, 16); part += __shfl_xor(part, 32);
;                 if (fq == 0) __hip_atomic_fetch_add(SS + row, (u64)(part * SSF), __ATOMIC_RELAXED, __HIP_MEMORY_SCOPE_AGENT); }
.LBB0_1072:
	s_or_b64 exec, exec, s[16:17]
	v_add_u32_e32 v40, 0xa0, v140
	v_ashrrev_i32_e32 v41, 31, v40
	s_waitcnt lgkmcnt(0)
	v_lshlrev_b64 v[32:33], 12, v[40:41]
	v_lshl_add_u64 v[32:33], s[48:49], 0, v[32:33]
	v_lshl_add_u64 v[42:43], v[138:139], 2, v[32:33]
	v_lshlrev_b64 v[40:41], 11, v[40:41]
	v_lshl_add_u64 v[40:41], s[14:15], 0, v[40:41]
	v_lshl_add_u64 v[40:41], v[138:139], 1, v[40:41]
	s_waitcnt vmcnt(22)
	v_pk_add_f32 v[30:31], v[30:31], v[168:169]
	v_pk_add_f32 v[28:29], v[28:29], v[166:167]
	v_pk_add_f32 v[26:27], v[26:27], v[172:173]
	v_pk_add_f32 v[24:25], v[24:25], v[170:171]
	v_cvt_pk_bf16_f32 v32, v28, v29
	v_cvt_pk_bf16_f32 v33, v30, v31
	v_cvt_pk_bf16_f32 v34, v24, v25
	v_cvt_pk_bf16_f32 v35, v26, v27
	global_store_dwordx4 v[42:43], v[28:31], off
	global_store_dwordx4 v[42:43], v[24:27], off offset:16
	global_store_dwordx4 v[40:41], v[32:35], off
	s_nop 1
	v_mul_f32_e32 v29, v29, v29
	v_mul_f32_e32 v31, v31, v31
	v_mul_f32_e32 v25, v25, v25
	v_fmac_f32_e32 v29, v28, v28
	v_fmac_f32_e32 v31, v30, v30
	v_mul_f32_e32 v27, v27, v27
	v_fmac_f32_e32 v25, v24, v24
	v_add_f32_e32 v24, v29, v31
	v_fmac_f32_e32 v27, v26, v26
	v_add_f32_e32 v24, v25, v24
	v_add_f32_e32 v28, v27, v24
	v_pk_add_f32 v[22:23], v[22:23], v[176:177]
	v_pk_add_f32 v[20:21], v[20:21], v[174:175]
	v_pk_add_f32 v[24:25], v[16:17], v[178:179]
	v_mul_f32_e32 v16, v21, v21
	v_mul_f32_e32 v17, v23, v23
	v_pk_add_f32 v[26:27], v[18:19], v[180:181]
	v_mul_f32_e32 v18, v25, v25
	v_fmac_f32_e32 v16, v20, v20
	v_fmac_f32_e32 v17, v22, v22
	v_mul_f32_e32 v19, v27, v27
	v_fmac_f32_e32 v18, v24, v24
	v_add_f32_e32 v16, v16, v17
	v_add_f32_e32 v16, v18, v16
	v_fmac_f32_e32 v19, v26, v26
	v_add_f32_e32 v16, v19, v16
	v_add_f32_e32 v16, v28, v16
	ds_bpermute_b32 v17, v121, v16
	global_store_dwordx4 v[42:43], v[20:23], off offset:512
	global_store_dwordx4 v[42:43], v[24:27], off offset:528
	v_cvt_pk_bf16_f32 v18, v20, v21
	v_cvt_pk_bf16_f32 v19, v22, v23
	v_cvt_pk_bf16_f32 v20, v24, v25
	s_waitcnt lgkmcnt(0)
	v_add_f32_e32 v16, v16, v17
	ds_bpermute_b32 v17, v120, v16
	v_cvt_pk_bf16_f32 v21, v26, v27
	global_store_dwordx4 v[40:41], v[18:21], off offset:256
	s_and_saveexec_b64 s[16:17], s[42:43]
	s_cbranch_execz .LBB0_1074
	s_waitcnt lgkmcnt(0)
	v_add_f32_e32 v16, v16, v17
	v_mul_f32_e32 v16, 0x4b800000, v16
	v_trunc_f32_e32 v16, v16
	v_mul_f32_e32 v17, 0x2f800000, v16
	v_floor_f32_e32 v17, v17
	v_fmac_f32_e32 v16, 0xcf800000, v17
	v_cvt_u32_f32_e32 v16, v16
	v_cvt_u32_f32_e32 v17, v17
	global_atomic_add_x2 v[112:113], v[16:17], off offset:1280
.LBB0_1074:
	s_or_b64 exec, exec, s[16:17]
	v_add_u32_e32 v16, 0xb0, v140
	s_waitcnt lgkmcnt(0)
	v_ashrrev_i32_e32 v17, 31, v16
	v_lshlrev_b64 v[18:19], 12, v[16:17]
	v_lshl_add_u64 v[18:19], s[48:49], 0, v[18:19]
	v_lshlrev_b64 v[16:17], 11, v[16:17]
	v_lshl_add_u64 v[24:25], v[138:139], 2, v[18:19]
	v_lshl_add_u64 v[16:17], s[14:15], 0, v[16:17]
	v_lshl_add_u64 v[26:27], v[138:139], 1, v[16:17]
	s_waitcnt vmcnt(18)
	v_pk_add_f32 v[10:11], v[10:11], v[188:189]
	v_pk_add_f32 v[14:15], v[14:15], v[184:185]
	v_pk_add_f32 v[12:13], v[12:13], v[182:183]
	v_pk_add_f32 v[8:9], v[8:9], v[186:187]
	global_store_dwordx4 v[24:25], v[12:15], off
	global_store_dwordx4 v[24:25], v[8:11], off offset:16
	v_cvt_pk_bf16_f32 v16, v12, v13
	v_mul_f32_e32 v13, v13, v13
	v_fmac_f32_e32 v13, v12, v12
	v_mul_f32_e32 v12, v15, v15
	v_cvt_pk_bf16_f32 v18, v8, v9
	v_fmac_f32_e32 v12, v14, v14
	v_mul_f32_e32 v9, v9, v9
	v_add_f32_e32 v12, v13, v12
	v_fmac_f32_e32 v9, v8, v8
	v_cvt_pk_bf16_f32 v17, v14, v15
	v_cvt_pk_bf16_f32 v19, v10, v11
	v_add_f32_e32 v8, v9, v12
	v_mul_f32_e32 v9, v11, v11
	global_store_dwordx4 v[26:27], v[16:19], off
	v_fmac_f32_e32 v9, v10, v10
	s_nop 0
	v_add_f32_e32 v16, v9, v8
	s_nop 1
	v_pk_add_f32 v[2:3], v[2:3], v[196:197]
	v_pk_add_f32 v[6:7], v[6:7], v[192:193]
	v_pk_add_f32 v[4:5], v[4:5], v[190:191]
	v_pk_add_f32 v[0:1], v[0:1], v[194:195]
	global_store_dwordx4 v[24:25], v[4:7], off offset:512
	global_store_dwordx4 v[24:25], v[0:3], off offset:528
	v_cvt_pk_bf16_f32 v8, v4, v5
	v_mul_f32_e32 v5, v5, v5
	v_fmac_f32_e32 v5, v4, v4
	v_mul_f32_e32 v4, v7, v7
	v_cvt_pk_bf16_f32 v10, v0, v1
	v_fmac_f32_e32 v4, v6, v6
	v_mul_f32_e32 v1, v1, v1
	v_add_f32_e32 v4, v5, v4
	v_fmac_f32_e32 v1, v0, v0
	v_add_f32_e32 v0, v1, v4
	v_mul_f32_e32 v1, v3, v3
	v_fmac_f32_e32 v1, v2, v2
	v_add_f32_e32 v0, v1, v0
	v_add_f32_e32 v0, v16, v0
	ds_bpermute_b32 v1, v121, v0
	v_cvt_pk_bf16_f32 v9, v6, v7
	v_cvt_pk_bf16_f32 v11, v2, v3
	global_store_dwordx4 v[26:27], v[8:11], off offset:256
	s_waitcnt lgkmcnt(0)
	v_add_f32_e32 v0, v0, v1
	ds_bpermute_b32 v1, v120, v0
	s_and_saveexec_b64 s[16:17], s[42:43]
	s_cbranch_execz .LBB0_1076
	s_waitcnt lgkmcnt(0)
	v_add_f32_e32 v0, v0, v1
	v_mul_f32_e32 v0, 0x4b800000, v0
	v_trunc_f32_e32 v0, v0
	v_mul_f32_e32 v1, 0x2f800000, v0
	v_floor_f32_e32 v1, v1
	v_fmac_f32_e32 v0, 0xcf800000, v1
	v_cvt_u32_f32_e32 v0, v0
	v_cvt_u32_f32_e32 v1, v1
	global_atomic_add_x2 v[112:113], v[0:1], off offset:1408

; #define PG8_WAIT_V(n) asm volatile("s_waitcnt vmcnt(" #n ")" ::: "memory")
; #define PG8_BAR __builtin_amdgcn_s_barrier()
; template <class Epi, bool ALIGN_EPI = true>
; __device__ __forceinline__ void gemm_phase(LAS unsigned char* lds, const Gemm g, const StaticOrder& S, const Epi& E, int wave_k) {
;     ...
;     PG8_WAIT_V(0);
;     if constexpr (!ALIGN_EPI) { if (wr == 0) PG8_BAR; }
;     PG8_BAR;
; __device__ __forceinline__ void xcd_barrier_head(const XcdBarrier& b) {
;     asm volatile("s_waitcnt vmcnt(0)" ::: "memory");
;     __syncthreads();
.LBB0_1079:
	v_readlane_b32 s54, v255, 0
	v_readlane_b32 s56, v255, 2
	v_readlane_b32 s55, v255, 1
	v_readlane_b32 s57, v255, 3
	s_barrier
.LBB0_1080:
	s_waitcnt lgkmcnt(0)
	s_barrier
	s_and_saveexec_b64 s[0:1], s[88:89]
	v_readlane_b32 s52, v255, 4
	v_readlane_b32 s34, v255, 6
	v_readlane_b32 s36, v255, 8
	v_readlane_b32 s53, v255, 5
	v_readlane_b32 s35, v255, 7
	v_readlane_b32 s37, v255, 9
	s_cbranch_execz .LBB0_1132
	v_readlane_b32 s2, v254, 50
	s_waitcnt vmcnt(0) expcnt(0) lgkmcnt(0)
	s_nop 0
	v_mov_b32_e32 v0, s2
	ds_read_b32 v2, v0
	v_readlane_b32 s2, v254, 51
	s_waitcnt lgkmcnt(0)
	v_cmp_ne_u32_e32 vcc, 0, v2
	v_mov_b32_e32 v0, s2
	ds_read_b32 v0, v0
	s_cbranch_vccnz .LBB0_1096
	s_mov_b32 s18, 1
	s_branch .LBB0_1084

; __device__ __forceinline__ unsigned cvtpk(float lo, float hi) { f32x2_t v = {lo, hi}; bf16x2_t b = __builtin_convertvector(v, bf16x2_t); return __builtin_bit_cast(unsigned, b); }
;     __device__ __forceinline__ void operator()(const Acc& acc, const Unit& u, int wr, int wc, int fr, int fq) const {
;         const int row0 = u.pm * BM + wr * 64 + fr, col0 = u.pn * BM + wc * 32 + 8 * fq;
; #pragma unroll
;         for (int ai = 0; ai < 2; ++ai)
; #pragma unroll
;             for (int m = 0; m < 4; ++m) { const int row = row0 + ai * HALF + m * 16; float* rp = X + (size_t)row * DM + col0; const float* ip = Xin + (size_t)row * DM + col0; bf16_t* bp = XB + (size_t)row * DM + col0; float part = 0.f;
; #pragma unroll
;                 for (int bj = 0; bj < 2; ++bj) { f32x4* p = (f32x4*)(rp + bj * HALF); const f32x4* q = (const f32x4*)(ip + bj * HALF); f32x4 a = q[0], b = q[1]; a += acc[ai][bj][m][0] * scale; b += acc[ai][bj][m][1] * scale; p[0] = a; p[1] = b;
;                     *(u32x4*)(bp + bj * HALF) = (u32x4){cvtpk(a[0], a[1]), cvtpk(a[2], a[3]), cvtpk(b[0], b[1]), cvtpk(b[2], b[3])};
;                     part += (a[0] * a[0] + a[1] * a[1]) + (a[2] * a[2] + a[3] * a[3]) + (b[0] * b[0] + b[1] * b[1]) + (b[2] * b[2] + b[3] * b[3]); }
;                 part += __shfl_xor(part, 16); part += __shfl_xor(part, 32);
;                 if (fq == 0) __hip_atomic_fetch_add(SS + row, (u64)(part * SSF), __ATOMIC_RELAXED, __HIP_MEMORY_SCOPE_AGENT); }
.LBB0_1260:
	v_lshl_add_u32 v140, s64, 8, v142
	v_ashrrev_i32_e32 v141, 31, v140
	v_lshl_or_b32 v138, s65, 8, v144
	v_lshlrev_b64 v[146:147], 12, v[140:141]
	v_ashrrev_i32_e32 v139, 31, v138
	v_lshl_add_u64 v[146:147], s[48:49], 0, v[146:147]
	v_lshl_add_u64 v[158:159], v[138:139], 2, v[146:147]
	v_mov_b64_e32 v[218:219], v[158:159]
	global_load_dwordx4 v[166:169], v[218:219], off
	global_load_dwordx4 v[170:173], v[218:219], off offset:16
	global_load_dwordx4 v[174:177], v[218:219], off offset:512
	global_load_dwordx4 v[178:181], v[218:219], off offset:528
	v_mov_b32_e32 v220, 0x10000
	v_mov_b32_e32 v221, 0
	v_lshl_add_u64 v[220:221], v[220:221], 0, v[218:219]
	global_load_dwordx4 v[182:185], v[220:221], off
	global_load_dwordx4 v[186:189], v[220:221], off offset:16
	global_load_dwordx4 v[190:193], v[220:221], off offset:512
	global_load_dwordx4 v[194:197], v[220:221], off offset:528
	v_mov_b32_e32 v220, 0x20000
	v_mov_b32_e32 v221, 0
	v_lshl_add_u64 v[220:221], v[220:221], 0, v[218:219]
	global_load_dwordx4 v[198:201], v[220:221], off
	global_load_dwordx4 v[202:205], v[220:221], off offset:16
	global_load_dwordx4 v[206:209], v[220:221], off offset:512
	global_load_dwordx4 v[210:213], v[220:221], off offset:528
	v_lshlrev_b64 v[154:155], 11, v[140:141]
	v_lshl_add_u64 v[154:155], s[14:15], 0, v[154:155]
	v_lshl_add_u64 v[162:163], v[138:139], 1, v[154:155]
	s_waitcnt vmcnt(8)
	v_pk_fma_f32 v[126:127], v[126:127], 0.5, v[168:169] op_sel_hi:[1,0,1]
	v_pk_fma_f32 v[124:125], v[124:125], 0.5, v[166:167] op_sel_hi:[1,0,1]
	v_pk_fma_f32 v[148:149], v[122:123], 0.5, v[172:173] op_sel_hi:[1,0,1]
	v_pk_fma_f32 v[146:147], v[120:121], 0.5, v[170:171] op_sel_hi:[1,0,1]
	v_cvt_pk_bf16_f32 v120, v124, v125
	v_cvt_pk_bf16_f32 v121, v126, v127
	v_cvt_pk_bf16_f32 v122, v146, v147
	v_cvt_pk_bf16_f32 v123, v148, v149
	global_store_dwordx4 v[158:159], v[124:127], off
	global_store_dwordx4 v[158:159], v[146:149], off offset:16
	global_store_dwordx4 v[162:163], v[120:123], off
	s_nop 1
	v_and_b32_e32 v121, 64, v229
	v_xor_b32_e32 v120, 16, v229
	v_add_u32_e32 v121, 64, v121
	v_xor_b32_e32 v122, 32, v229
	v_cmp_lt_i32_e32 vcc, v120, v121
	v_mul_f32_e32 v123, v127, v127
	v_fmac_f32_e32 v123, v126, v126
	v_cndmask_b32_e32 v120, v229, v120, vcc
	v_cmp_lt_i32_e32 vcc, v122, v121
	v_mul_f32_e32 v127, v149, v149
	v_fmac_f32_e32 v127, v148, v148
	v_cndmask_b32_e32 v121, v229, v122, vcc
	v_mul_f32_e32 v122, v125, v125
	v_mul_f32_e32 v125, v147, v147
	v_fmac_f32_e32 v122, v124, v124
	v_fmac_f32_e32 v125, v146, v146
	v_add_f32_e32 v122, v122, v123
	v_add_f32_e32 v122, v125, v122
	v_add_f32_e32 v126, v127, v122
	v_lshlrev_b32_e32 v120, 2, v120
	v_pk_fma_f32 v[118:119], v[118:119], 0.5, v[176:177] op_sel_hi:[1,0,1]
	v_pk_fma_f32 v[116:117], v[116:117], 0.5, v[174:175] op_sel_hi:[1,0,1]
	v_pk_fma_f32 v[122:123], v[112:113], 0.5, v[178:179] op_sel_hi:[1,0,1]
	v_mul_f32_e32 v112, v117, v117
	v_mul_f32_e32 v113, v119, v119
	v_pk_fma_f32 v[124:125], v[114:115], 0.5, v[180:181] op_sel_hi:[1,0,1]
	v_mov_b32_e32 v220, 0x30000
	v_mov_b32_e32 v221, 0
	v_lshl_add_u64 v[220:221], v[220:221], 0, v[218:219]
	global_load_dwordx4 v[166:169], v[220:221], off
	global_load_dwordx4 v[170:173], v[220:221], off offset:16
	global_load_dwordx4 v[174:177], v[220:221], off offset:512
	global_load_dwordx4 v[178:181], v[220:221], off offset:528
	v_mul_f32_e32 v114, v123, v123
	v_fmac_f32_e32 v112, v116, v116
	v_fmac_f32_e32 v113, v118, v118
	v_mul_f32_e32 v115, v125, v125
	v_fmac_f32_e32 v114, v122, v122
	v_add_f32_e32 v112, v112, v113
	v_add_f32_e32 v112, v114, v112
	v_fmac_f32_e32 v115, v124, v124
	v_add_f32_e32 v112, v115, v112
	v_add_f32_e32 v112, v126, v112
	ds_bpermute_b32 v113, v120, v112
	v_lshlrev_b32_e32 v114, 2, v121
	global_store_dwordx4 v[158:159], v[116:119], off offset:512
	global_store_dwordx4 v[158:159], v[122:125], off offset:528
	s_waitcnt lgkmcnt(0)
	v_add_f32_e32 v112, v112, v113
	ds_bpermute_b32 v113, v114, v112
	v_cvt_pk_bf16_f32 v116, v116, v117
	v_cvt_pk_bf16_f32 v117, v118, v119
	v_cvt_pk_bf16_f32 v118, v122, v123
	v_cvt_pk_bf16_f32 v119, v124, v125
	global_store_dwordx4 v[162:163], v[116:119], off offset:256
	s_and_saveexec_b64 s[16:17], s[40:41]
	s_cbranch_execz .LBB0_1262
	s_waitcnt lgkmcnt(0)
	v_add_f32_e32 v112, v112, v113
	v_mul_f32_e32 v112, 0x4b800000, v112
	v_trunc_f32_e32 v112, v112
	v_mul_f32_e32 v113, 0x2f800000, v112
	v_floor_f32_e32 v113, v113
	v_fmac_f32_e32 v112, 0xcf800000, v113
	v_cvt_u32_f32_e32 v112, v112
	v_cvt_u32_f32_e32 v113, v113
	v_lshl_add_u64 v[116:117], v[140:141], 3, s[18:19]
	global_atomic_add_x2 v[116:117], v[112:113], off
; __device__ __forceinline__ unsigned cvtpk(float lo, float hi) { f32x2_t v = {lo, hi}; bf16x2_t b = __builtin_convertvector(v, bf16x2_t); return __builtin_bit_cast(unsigned, b); }
;     __device__ __forceinline__ void operator()(const Acc& acc, const Unit& u, int wr, int wc, int fr, int fq) const {
;         const int row0 = u.pm * BM + wr * 64 + fr, col0 = u.pn * BM + wc * 32 + 8 * fq;
; #pragma unroll
;         for (int ai = 0; ai < 2; ++ai)
; #pragma unroll
;             for (int m = 0; m < 4; ++m) { const int row = row0 + ai * HALF + m * 16; float* rp = X + (size_t)row * DM + col0; const float* ip = Xin + (size_t)row * DM + col0; bf16_t* bp = XB + (size_t)row * DM + col0; float part = 0.f;
; #pragma unroll
;                 for (int bj = 0; bj < 2; ++bj) { f32x4* p = (f32x4*)(rp + bj * HALF); const f32x4* q = (const f32x4*)(ip + bj * HALF); f32x4 a = q[0], b = q[1]; a += acc[ai][bj][m][0] * scale; b += acc[ai][bj][m][1] * scale; p[0] = a; p[1] = b;
;                     *(u32x4*)(bp + bj * HALF) = (u32x4){cvtpk(a[0], a[1]), cvtpk(a[2], a[3]), cvtpk(b[0], b[1]), cvtpk(b[2], b[3])};
;                     part += (a[0] * a[0] + a[1] * a[1]) + (a[2] * a[2] + a[3] * a[3]) + (b[0] * b[0] + b[1] * b[1]) + (b[2] * b[2] + b[3] * b[3]); }
;                 part += __shfl_xor(part, 16); part += __shfl_xor(part, 32);
;                 if (fq == 0) __hip_atomic_fetch_add(SS + row, (u64)(part * SSF), __ATOMIC_RELAXED, __HIP_MEMORY_SCOPE_AGENT); }
.LBB0_1262:
	s_or_b64 exec, exec, s[16:17]
	v_or_b32_e32 v112, 16, v140
	s_waitcnt lgkmcnt(0)
	v_ashrrev_i32_e32 v113, 31, v112
	v_lshlrev_b64 v[116:117], 12, v[112:113]
	v_lshl_add_u64 v[116:117], s[48:49], 0, v[116:117]
	v_lshl_add_u64 v[126:127], v[138:139], 2, v[116:117]
	v_lshlrev_b64 v[146:147], 11, v[112:113]
	v_lshl_add_u64 v[146:147], s[14:15], 0, v[146:147]
	v_lshl_add_u64 v[146:147], v[138:139], 1, v[146:147]
	s_waitcnt vmcnt(15)
	v_pk_fma_f32 v[110:111], v[110:111], 0.5, v[184:185] op_sel_hi:[1,0,1]
	v_pk_fma_f32 v[108:109], v[108:109], 0.5, v[182:183] op_sel_hi:[1,0,1]
	v_pk_fma_f32 v[106:107], v[106:107], 0.5, v[188:189] op_sel_hi:[1,0,1]
	v_pk_fma_f32 v[104:105], v[104:105], 0.5, v[186:187] op_sel_hi:[1,0,1]
	v_cvt_pk_bf16_f32 v116, v108, v109
	v_cvt_pk_bf16_f32 v117, v110, v111
	v_cvt_pk_bf16_f32 v118, v104, v105
	v_cvt_pk_bf16_f32 v119, v106, v107
	global_store_dwordx4 v[126:127], v[108:111], off
	global_store_dwordx4 v[126:127], v[104:107], off offset:16
	global_store_dwordx4 v[146:147], v[116:119], off
	s_nop 1
	v_mul_f32_e32 v109, v109, v109
	v_mul_f32_e32 v111, v111, v111
	v_mul_f32_e32 v105, v105, v105
	v_fmac_f32_e32 v109, v108, v108
	v_fmac_f32_e32 v111, v110, v110
	v_mul_f32_e32 v107, v107, v107
	v_fmac_f32_e32 v105, v104, v104
	v_add_f32_e32 v104, v109, v111
	v_fmac_f32_e32 v107, v106, v106
	v_add_f32_e32 v104, v105, v104
	v_add_f32_e32 v108, v107, v104
	v_pk_fma_f32 v[102:103], v[102:103], 0.5, v[192:193] op_sel_hi:[1,0,1]
	v_pk_fma_f32 v[100:101], v[100:101], 0.5, v[190:191] op_sel_hi:[1,0,1]
	v_pk_fma_f32 v[104:105], v[96:97], 0.5, v[194:195] op_sel_hi:[1,0,1]
	v_mul_f32_e32 v96, v101, v101
	v_mul_f32_e32 v97, v103, v103
	v_pk_fma_f32 v[106:107], v[98:99], 0.5, v[196:197] op_sel_hi:[1,0,1]
	v_mov_b32_e32 v220, 0x80000
	v_mov_b32_e32 v221, 0
	v_lshl_add_u64 v[220:221], v[220:221], 0, v[218:219]
	global_load_dwordx4 v[182:185], v[220:221], off
	global_load_dwordx4 v[186:189], v[220:221], off offset:16
	global_load_dwordx4 v[190:193], v[220:221], off offset:512
	global_load_dwordx4 v[194:197], v[220:221], off offset:528
	v_mul_f32_e32 v98, v105, v105
	v_fmac_f32_e32 v96, v100, v100
	v_fmac_f32_e32 v97, v102, v102
	v_mul_f32_e32 v99, v107, v107
	v_fmac_f32_e32 v98, v104, v104
	v_add_f32_e32 v96, v96, v97
	v_add_f32_e32 v96, v98, v96
	v_fmac_f32_e32 v99, v106, v106
	v_add_f32_e32 v96, v99, v96
	v_add_f32_e32 v96, v108, v96
	ds_bpermute_b32 v97, v120, v96
	global_store_dwordx4 v[126:127], v[100:103], off offset:512
	global_store_dwordx4 v[126:127], v[104:107], off offset:528
	v_cvt_pk_bf16_f32 v98, v100, v101
	v_cvt_pk_bf16_f32 v99, v102, v103
	v_cvt_pk_bf16_f32 v100, v104, v105
	s_waitcnt lgkmcnt(0)
	v_add_f32_e32 v96, v96, v97
	ds_bpermute_b32 v97, v114, v96
	v_cvt_pk_bf16_f32 v101, v106, v107
	global_store_dwordx4 v[146:147], v[98:101], off offset:256
	s_and_saveexec_b64 s[16:17], s[40:41]
	s_cbranch_execz .LBB0_1264
	s_waitcnt lgkmcnt(0)
	v_add_f32_e32 v96, v96, v97
	v_mul_f32_e32 v96, 0x4b800000, v96
	v_trunc_f32_e32 v96, v96
	v_mul_f32_e32 v97, 0x2f800000, v96
	v_floor_f32_e32 v97, v97
	v_fmac_f32_e32 v96, 0xcf800000, v97
	v_cvt_u32_f32_e32 v96, v96
	v_cvt_u32_f32_e32 v97, v97
	v_lshl_add_u64 v[98:99], v[112:113], 3, s[18:19]
	global_atomic_add_x2 v[98:99], v[96:97], off
.LBB0_1264:
	s_or_b64 exec, exec, s[16:17]
	v_or_b32_e32 v96, 32, v140
	s_waitcnt lgkmcnt(0)
	v_ashrrev_i32_e32 v97, 31, v96
	v_lshlrev_b64 v[98:99], 12, v[96:97]
	v_lshl_add_u64 v[98:99], s[48:49], 0, v[98:99]
	v_lshl_add_u64 v[106:107], v[138:139], 2, v[98:99]
	v_lshlrev_b64 v[108:109], 11, v[96:97]
	v_lshl_add_u64 v[108:109], s[14:15], 0, v[108:109]
	v_lshl_add_u64 v[108:109], v[138:139], 1, v[108:109]
	s_waitcnt vmcnt(22)
	v_pk_fma_f32 v[94:95], v[94:95], 0.5, v[200:201] op_sel_hi:[1,0,1]
	v_pk_fma_f32 v[92:93], v[92:93], 0.5, v[198:199] op_sel_hi:[1,0,1]
	v_pk_fma_f32 v[90:91], v[90:91], 0.5, v[204:205] op_sel_hi:[1,0,1]
	v_pk_fma_f32 v[88:89], v[88:89], 0.5, v[202:203] op_sel_hi:[1,0,1]
	v_cvt_pk_bf16_f32 v98, v92, v93
	v_cvt_pk_bf16_f32 v99, v94, v95
	v_cvt_pk_bf16_f32 v100, v88, v89
	v_cvt_pk_bf16_f32 v101, v90, v91
	global_store_dwordx4 v[106:107], v[92:95], off
	global_store_dwordx4 v[106:107], v[88:91], off offset:16
	global_store_dwordx4 v[108:109], v[98:101], off
	s_nop 1
	v_mul_f32_e32 v93, v93, v93
	v_mul_f32_e32 v95, v95, v95
	v_mul_f32_e32 v89, v89, v89
	v_fmac_f32_e32 v93, v92, v92
	v_fmac_f32_e32 v95, v94, v94
	v_mul_f32_e32 v91, v91, v91
	v_fmac_f32_e32 v89, v88, v88
	v_add_f32_e32 v88, v93, v95
	v_fmac_f32_e32 v91, v90, v90
	v_add_f32_e32 v88, v89, v88
	v_add_f32_e32 v92, v91, v88
	v_pk_fma_f32 v[86:87], v[86:87], 0.5, v[208:209] op_sel_hi:[1,0,1]
	v_pk_fma_f32 v[84:85], v[84:85], 0.5, v[206:207] op_sel_hi:[1,0,1]
	v_pk_fma_f32 v[88:89], v[80:81], 0.5, v[210:211] op_sel_hi:[1,0,1]
	v_mul_f32_e32 v80, v85, v85
	v_mul_f32_e32 v81, v87, v87
	v_pk_fma_f32 v[90:91], v[82:83], 0.5, v[212:213] op_sel_hi:[1,0,1]
	v_mov_b32_e32 v220, 0x90000
	v_mov_b32_e32 v221, 0
	v_lshl_add_u64 v[220:221], v[220:221], 0, v[218:219]
	global_load_dwordx4 v[198:201], v[220:221], off
	global_load_dwordx4 v[202:205], v[220:221], off offset:16
	global_load_dwordx4 v[206:209], v[220:221], off offset:512
	global_load_dwordx4 v[210:213], v[220:221], off offset:528
	v_mul_f32_e32 v82, v89, v89
	v_fmac_f32_e32 v80, v84, v84
	v_fmac_f32_e32 v81, v86, v86
	v_mul_f32_e32 v83, v91, v91
	v_fmac_f32_e32 v82, v88, v88
	v_add_f32_e32 v80, v80, v81
	v_add_f32_e32 v80, v82, v80
	v_fmac_f32_e32 v83, v90, v90
	v_add_f32_e32 v80, v83, v80
	v_add_f32_e32 v80, v92, v80
	ds_bpermute_b32 v81, v120, v80
	global_store_dwordx4 v[106:107], v[84:87], off offset:512
	global_store_dwordx4 v[106:107], v[88:91], off offset:528
	v_cvt_pk_bf16_f32 v82, v84, v85
	v_cvt_pk_bf16_f32 v83, v86, v87
	v_cvt_pk_bf16_f32 v84, v88, v89
	s_waitcnt lgkmcnt(0)
	v_add_f32_e32 v80, v80, v81
	ds_bpermute_b32 v81, v114, v80
	v_cvt_pk_bf16_f32 v85, v90, v91
	global_store_dwordx4 v[108:109], v[82:85], off offset:256
	s_and_saveexec_b64 s[16:17], s[40:41]
	s_cbranch_execz .LBB0_1266
	s_waitcnt lgkmcnt(0)
	v_add_f32_e32 v80, v80, v81
	v_mul_f32_e32 v80, 0x4b800000, v80
	v_trunc_f32_e32 v80, v80
	v_mul_f32_e32 v81, 0x2f800000, v80
	v_floor_f32_e32 v81, v81
	v_fmac_f32_e32 v80, 0xcf800000, v81
	v_cvt_u32_f32_e32 v80, v80
	v_cvt_u32_f32_e32 v81, v81
	v_lshl_add_u64 v[82:83], v[96:97], 3, s[18:19]
	global_atomic_add_x2 v[82:83], v[80:81], off
; __device__ __forceinline__ unsigned cvtpk(float lo, float hi) { f32x2_t v = {lo, hi}; bf16x2_t b = __builtin_convertvector(v, bf16x2_t); return __builtin_bit_cast(unsigned, b); }
;     __device__ __forceinline__ void operator()(const Acc& acc, const Unit& u, int wr, int wc, int fr, int fq) const {
;         const int row0 = u.pm * BM + wr * 64 + fr, col0 = u.pn * BM + wc * 32 + 8 * fq;
; #pragma unroll
;         for (int ai = 0; ai < 2; ++ai)
; #pragma unroll
;             for (int m = 0; m < 4; ++m) { const int row = row0 + ai * HALF + m * 16; float* rp = X + (size_t)row * DM + col0; const float* ip = Xin + (size_t)row * DM + col0; bf16_t* bp = XB + (size_t)row * DM + col0; float part = 0.f;
; #pragma unroll
;                 for (int bj = 0; bj < 2; ++bj) { f32x4* p = (f32x4*)(rp + bj * HALF); const f32x4* q = (const f32x4*)(ip + bj * HALF); f32x4 a = q[0], b = q[1]; a += acc[ai][bj][m][0] * scale; b += acc[ai][bj][m][1] * scale; p[0] = a; p[1] = b;
;                     *(u32x4*)(bp + bj * HALF) = (u32x4){cvtpk(a[0], a[1]), cvtpk(a[2], a[3]), cvtpk(b[0], b[1]), cvtpk(b[2], b[3])};
;                     part += (a[0] * a[0] + a[1] * a[1]) + (a[2] * a[2] + a[3] * a[3]) + (b[0] * b[0] + b[1] * b[1]) + (b[2] * b[2] + b[3] * b[3]); }
;                 part += __shfl_xor(part, 16); part += __shfl_xor(part, 32);
;                 if (fq == 0) __hip_atomic_fetch_add(SS + row, (u64)(part * SSF), __ATOMIC_RELAXED, __HIP_MEMORY_SCOPE_AGENT); }
.LBB0_1266:
	s_or_b64 exec, exec, s[16:17]
	v_or_b32_e32 v80, 48, v140
	s_waitcnt lgkmcnt(0)
	v_ashrrev_i32_e32 v81, 31, v80
	v_lshlrev_b64 v[82:83], 12, v[80:81]
	v_lshl_add_u64 v[82:83], s[48:49], 0, v[82:83]
	v_lshl_add_u64 v[90:91], v[138:139], 2, v[82:83]
	v_lshlrev_b64 v[92:93], 11, v[80:81]
	v_lshl_add_u64 v[92:93], s[14:15], 0, v[92:93]
	v_lshl_add_u64 v[92:93], v[138:139], 1, v[92:93]
	s_waitcnt vmcnt(26)
	v_pk_fma_f32 v[78:79], v[78:79], 0.5, v[168:169] op_sel_hi:[1,0,1]
	v_pk_fma_f32 v[76:77], v[76:77], 0.5, v[166:167] op_sel_hi:[1,0,1]
	v_pk_fma_f32 v[74:75], v[74:75], 0.5, v[172:173] op_sel_hi:[1,0,1]
	v_pk_fma_f32 v[72:73], v[72:73], 0.5, v[170:171] op_sel_hi:[1,0,1]
	v_cvt_pk_bf16_f32 v82, v76, v77
	v_cvt_pk_bf16_f32 v83, v78, v79
	v_cvt_pk_bf16_f32 v84, v72, v73
	v_cvt_pk_bf16_f32 v85, v74, v75
	global_store_dwordx4 v[90:91], v[76:79], off
	global_store_dwordx4 v[90:91], v[72:75], off offset:16
	global_store_dwordx4 v[92:93], v[82:85], off
	s_nop 1
	v_mul_f32_e32 v77, v77, v77
	v_mul_f32_e32 v79, v79, v79
	v_mul_f32_e32 v73, v73, v73
	v_fmac_f32_e32 v77, v76, v76
	v_fmac_f32_e32 v79, v78, v78
	v_mul_f32_e32 v75, v75, v75
	v_fmac_f32_e32 v73, v72, v72
	v_add_f32_e32 v72, v77, v79
	v_fmac_f32_e32 v75, v74, v74
	v_add_f32_e32 v72, v73, v72
	v_add_f32_e32 v76, v75, v72
	v_pk_fma_f32 v[70:71], v[70:71], 0.5, v[176:177] op_sel_hi:[1,0,1]
	v_pk_fma_f32 v[68:69], v[68:69], 0.5, v[174:175] op_sel_hi:[1,0,1]
	v_pk_fma_f32 v[72:73], v[64:65], 0.5, v[178:179] op_sel_hi:[1,0,1]
	v_mul_f32_e32 v64, v69, v69
	v_mul_f32_e32 v65, v71, v71
	v_pk_fma_f32 v[74:75], v[66:67], 0.5, v[180:181] op_sel_hi:[1,0,1]
	v_mov_b32_e32 v220, 0xa0000
	v_mov_b32_e32 v221, 0
	v_lshl_add_u64 v[220:221], v[220:221], 0, v[218:219]
	global_load_dwordx4 v[166:169], v[220:221], off
	global_load_dwordx4 v[170:173], v[220:221], off offset:16
	global_load_dwordx4 v[174:177], v[220:221], off offset:512
	global_load_dwordx4 v[178:181], v[220:221], off offset:528
	v_mul_f32_e32 v66, v73, v73
	v_fmac_f32_e32 v64, v68, v68
	v_fmac_f32_e32 v65, v70, v70
	v_mul_f32_e32 v67, v75, v75
	v_fmac_f32_e32 v66, v72, v72
	v_add_f32_e32 v64, v64, v65
	v_add_f32_e32 v64, v66, v64
	v_fmac_f32_e32 v67, v74, v74
	v_add_f32_e32 v64, v67, v64
	v_add_f32_e32 v64, v76, v64
	ds_bpermute_b32 v65, v120, v64
	global_store_dwordx4 v[90:91], v[68:71], off offset:512
	global_store_dwordx4 v[90:91], v[72:75], off offset:528
	v_cvt_pk_bf16_f32 v66, v68, v69
	v_cvt_pk_bf16_f32 v67, v70, v71
	v_cvt_pk_bf16_f32 v68, v72, v73
	s_waitcnt lgkmcnt(0)
	v_add_f32_e32 v64, v64, v65
	ds_bpermute_b32 v65, v114, v64
	v_cvt_pk_bf16_f32 v69, v74, v75
	global_store_dwordx4 v[92:93], v[66:69], off offset:256
	s_and_saveexec_b64 s[16:17], s[40:41]
	s_cbranch_execz .LBB0_1268
	s_waitcnt lgkmcnt(0)
	v_add_f32_e32 v64, v64, v65
	v_mul_f32_e32 v64, 0x4b800000, v64
	v_trunc_f32_e32 v64, v64
	v_mul_f32_e32 v65, 0x2f800000, v64
	v_floor_f32_e32 v65, v65
	v_fmac_f32_e32 v64, 0xcf800000, v65
	v_cvt_u32_f32_e32 v64, v64
	v_cvt_u32_f32_e32 v65, v65
	v_lshl_add_u64 v[66:67], v[80:81], 3, s[18:19]
	global_atomic_add_x2 v[66:67], v[64:65], off
.LBB0_1268:
	s_or_b64 exec, exec, s[16:17]
	v_add_u32_e32 v64, 0x80, v140
	s_waitcnt lgkmcnt(0)
	v_ashrrev_i32_e32 v65, 31, v64
	v_lshlrev_b64 v[66:67], 12, v[64:65]
	v_lshl_add_u64 v[66:67], s[48:49], 0, v[66:67]
	v_lshl_add_u64 v[74:75], v[138:139], 2, v[66:67]
	v_lshlrev_b64 v[76:77], 11, v[64:65]
	v_lshl_add_u64 v[76:77], s[14:15], 0, v[76:77]
	v_lshl_add_u64 v[76:77], v[138:139], 1, v[76:77]
	s_waitcnt vmcnt(26)
	v_pk_fma_f32 v[62:63], v[62:63], 0.5, v[184:185] op_sel_hi:[1,0,1]
	v_pk_fma_f32 v[60:61], v[60:61], 0.5, v[182:183] op_sel_hi:[1,0,1]
	v_pk_fma_f32 v[58:59], v[58:59], 0.5, v[188:189] op_sel_hi:[1,0,1]
	v_pk_fma_f32 v[56:57], v[56:57], 0.5, v[186:187] op_sel_hi:[1,0,1]
	v_cvt_pk_bf16_f32 v66, v60, v61
	v_cvt_pk_bf16_f32 v67, v62, v63
	v_cvt_pk_bf16_f32 v68, v56, v57
	v_cvt_pk_bf16_f32 v69, v58, v59
	global_store_dwordx4 v[74:75], v[60:63], off
	global_store_dwordx4 v[74:75], v[56:59], off offset:16
	global_store_dwordx4 v[76:77], v[66:69], off
	s_nop 1
	v_mul_f32_e32 v61, v61, v61
	v_mul_f32_e32 v63, v63, v63
	v_mul_f32_e32 v57, v57, v57
	v_fmac_f32_e32 v61, v60, v60
	v_fmac_f32_e32 v63, v62, v62
	v_mul_f32_e32 v59, v59, v59
	v_fmac_f32_e32 v57, v56, v56
	v_add_f32_e32 v56, v61, v63
	v_fmac_f32_e32 v59, v58, v58
	v_add_f32_e32 v56, v57, v56
	v_add_f32_e32 v60, v59, v56
	v_pk_fma_f32 v[54:55], v[54:55], 0.5, v[192:193] op_sel_hi:[1,0,1]
	v_pk_fma_f32 v[52:53], v[52:53], 0.5, v[190:191] op_sel_hi:[1,0,1]
	v_pk_fma_f32 v[56:57], v[48:49], 0.5, v[194:195] op_sel_hi:[1,0,1]
	v_mul_f32_e32 v48, v53, v53
	v_mul_f32_e32 v49, v55, v55
	v_pk_fma_f32 v[58:59], v[50:51], 0.5, v[196:197] op_sel_hi:[1,0,1]
	v_mov_b32_e32 v220, 0xb0000
	v_mov_b32_e32 v221, 0
	v_lshl_add_u64 v[220:221], v[220:221], 0, v[218:219]
	global_load_dwordx4 v[182:185], v[220:221], off
	global_load_dwordx4 v[186:189], v[220:221], off offset:16
	global_load_dwordx4 v[190:193], v[220:221], off offset:512
	global_load_dwordx4 v[194:197], v[220:221], off offset:528
	v_mul_f32_e32 v50, v57, v57
	v_fmac_f32_e32 v48, v52, v52
	v_fmac_f32_e32 v49, v54, v54
	v_mul_f32_e32 v51, v59, v59
	v_fmac_f32_e32 v50, v56, v56
	v_add_f32_e32 v48, v48, v49
	v_add_f32_e32 v48, v50, v48
	v_fmac_f32_e32 v51, v58, v58
	v_add_f32_e32 v48, v51, v48
	v_add_f32_e32 v48, v60, v48
	ds_bpermute_b32 v49, v120, v48
	global_store_dwordx4 v[74:75], v[52:55], off offset:512
	global_store_dwordx4 v[74:75], v[56:59], off offset:528
	v_cvt_pk_bf16_f32 v50, v52, v53
	v_cvt_pk_bf16_f32 v51, v54, v55
	v_cvt_pk_bf16_f32 v52, v56, v57
	s_waitcnt lgkmcnt(0)
	v_add_f32_e32 v48, v48, v49
	ds_bpermute_b32 v49, v114, v48
	v_cvt_pk_bf16_f32 v53, v58, v59
	global_store_dwordx4 v[76:77], v[50:53], off offset:256
	s_and_saveexec_b64 s[16:17], s[40:41]
	s_cbranch_execz .LBB0_1270
	s_waitcnt lgkmcnt(0)
	v_add_f32_e32 v48, v48, v49
	v_mul_f32_e32 v48, 0x4b800000, v48
	v_trunc_f32_e32 v48, v48
	v_mul_f32_e32 v49, 0x2f800000, v48
	v_floor_f32_e32 v49, v49
	v_fmac_f32_e32 v48, 0xcf800000, v49
	v_cvt_u32_f32_e32 v48, v48
	v_cvt_u32_f32_e32 v49, v49
	v_lshl_add_u64 v[50:51], v[64:65], 3, s[18:19]
	global_atomic_add_x2 v[50:51], v[48:49], off
; __device__ __forceinline__ unsigned cvtpk(float lo, float hi) { f32x2_t v = {lo, hi}; bf16x2_t b = __builtin_convertvector(v, bf16x2_t); return __builtin_bit_cast(unsigned, b); }
;     __device__ __forceinline__ void operator()(const Acc& acc, const Unit& u, int wr, int wc, int fr, int fq) const {
;         const int row0 = u.pm * BM + wr * 64 + fr, col0 = u.pn * BM + wc * 32 + 8 * fq;
; #pragma unroll
;         for (int ai = 0; ai < 2; ++ai)
; #pragma unroll
;             for (int m = 0; m < 4; ++m) { const int row = row0 + ai * HALF + m * 16; float* rp = X + (size_t)row * DM + col0; const float* ip = Xin + (size_t)row * DM + col0; bf16_t* bp = XB + (size_t)row * DM + col0; float part = 0.f;
; #pragma unroll
;                 for (int bj = 0; bj < 2; ++bj) { f32x4* p = (f32x4*)(rp + bj * HALF); const f32x4* q = (const f32x4*)(ip + bj * HALF); f32x4 a = q[0], b = q[1]; a += acc[ai][bj][m][0] * scale; b += acc[ai][bj][m][1] * scale; p[0] = a; p[1] = b;
;                     *(u32x4*)(bp + bj * HALF) = (u32x4){cvtpk(a[0], a[1]), cvtpk(a[2], a[3]), cvtpk(b[0], b[1]), cvtpk(b[2], b[3])};
;                     part += (a[0] * a[0] + a[1] * a[1]) + (a[2] * a[2] + a[3] * a[3]) + (b[0] * b[0] + b[1] * b[1]) + (b[2] * b[2] + b[3] * b[3]); }
;                 part += __shfl_xor(part, 16); part += __shfl_xor(part, 32);
;                 if (fq == 0) __hip_atomic_fetch_add(SS + row, (u64)(part * SSF), __ATOMIC_RELAXED, __HIP_MEMORY_SCOPE_AGENT); }
.LBB0_1270:
	s_or_b64 exec, exec, s[16:17]
	v_add_u32_e32 v48, 0x90, v140
	s_waitcnt lgkmcnt(0)
	v_ashrrev_i32_e32 v49, 31, v48
	v_lshlrev_b64 v[50:51], 12, v[48:49]
	v_lshl_add_u64 v[50:51], s[48:49], 0, v[50:51]
	v_lshl_add_u64 v[58:59], v[138:139], 2, v[50:51]
	v_lshlrev_b64 v[60:61], 11, v[48:49]
	v_lshl_add_u64 v[60:61], s[14:15], 0, v[60:61]
	v_lshl_add_u64 v[60:61], v[138:139], 1, v[60:61]
	s_waitcnt vmcnt(26)
	v_pk_fma_f32 v[46:47], v[46:47], 0.5, v[200:201] op_sel_hi:[1,0,1]
	v_pk_fma_f32 v[44:45], v[44:45], 0.5, v[198:199] op_sel_hi:[1,0,1]
	v_pk_fma_f32 v[42:43], v[42:43], 0.5, v[204:205] op_sel_hi:[1,0,1]
	v_pk_fma_f32 v[40:41], v[40:41], 0.5, v[202:203] op_sel_hi:[1,0,1]
	v_cvt_pk_bf16_f32 v50, v44, v45
	v_cvt_pk_bf16_f32 v51, v46, v47
	v_cvt_pk_bf16_f32 v52, v40, v41
	v_cvt_pk_bf16_f32 v53, v42, v43
	global_store_dwordx4 v[58:59], v[44:47], off
	global_store_dwordx4 v[58:59], v[40:43], off offset:16
	global_store_dwordx4 v[60:61], v[50:53], off
	s_nop 1
	v_mul_f32_e32 v45, v45, v45
	v_mul_f32_e32 v47, v47, v47
	v_mul_f32_e32 v41, v41, v41
	v_fmac_f32_e32 v45, v44, v44
	v_fmac_f32_e32 v47, v46, v46
	v_mul_f32_e32 v43, v43, v43
	v_fmac_f32_e32 v41, v40, v40
	v_add_f32_e32 v40, v45, v47
	v_fmac_f32_e32 v43, v42, v42
	v_add_f32_e32 v40, v41, v40
	v_add_f32_e32 v44, v43, v40
	v_pk_fma_f32 v[38:39], v[38:39], 0.5, v[208:209] op_sel_hi:[1,0,1]
	v_pk_fma_f32 v[36:37], v[36:37], 0.5, v[206:207] op_sel_hi:[1,0,1]
	v_pk_fma_f32 v[40:41], v[32:33], 0.5, v[210:211] op_sel_hi:[1,0,1]
	v_mul_f32_e32 v32, v37, v37
	v_mul_f32_e32 v33, v39, v39
	v_pk_fma_f32 v[42:43], v[34:35], 0.5, v[212:213] op_sel_hi:[1,0,1]
	v_mul_f32_e32 v34, v41, v41
	v_fmac_f32_e32 v32, v36, v36
	v_fmac_f32_e32 v33, v38, v38
	v_mul_f32_e32 v35, v43, v43
	v_fmac_f32_e32 v34, v40, v40
	v_add_f32_e32 v32, v32, v33
	v_add_f32_e32 v32, v34, v32
	v_fmac_f32_e32 v35, v42, v42
	v_add_f32_e32 v32, v35, v32
	v_add_f32_e32 v32, v44, v32
	ds_bpermute_b32 v33, v120, v32
	global_store_dwordx4 v[58:59], v[36:39], off offset:512
	global_store_dwordx4 v[58:59], v[40:43], off offset:528
	v_cvt_pk_bf16_f32 v34, v36, v37
	v_cvt_pk_bf16_f32 v35, v38, v39
	v_cvt_pk_bf16_f32 v36, v40, v41
	s_waitcnt lgkmcnt(0)
	v_add_f32_e32 v32, v32, v33
	ds_bpermute_b32 v33, v114, v32
	v_cvt_pk_bf16_f32 v37, v42, v43
	global_store_dwordx4 v[60:61], v[34:37], off offset:256
	s_and_saveexec_b64 s[16:17], s[40:41]
	s_cbranch_execz .LBB0_1272
	s_waitcnt lgkmcnt(0)
	v_add_f32_e32 v32, v32, v33
	v_mul_f32_e32 v32, 0x4b800000, v32
	v_trunc_f32_e32 v32, v32
	v_mul_f32_e32 v33, 0x2f800000, v32
	v_floor_f32_e32 v33, v33
	v_fmac_f32_e32 v32, 0xcf800000, v33
	v_cvt_u32_f32_e32 v32, v32
	v_cvt_u32_f32_e32 v33, v33
	v_lshl_add_u64 v[34:35], v[48:49], 3, s[18:19]
	global_atomic_add_x2 v[34:35], v[32:33], off
; __device__ __forceinline__ unsigned cvtpk(float lo, float hi) { f32x2_t v = {lo, hi}; bf16x2_t b = __builtin_convertvector(v, bf16x2_t); return __builtin_bit_cast(unsigned, b); }
;     __device__ __forceinline__ void operator()(const Acc& acc, const Unit& u, int wr, int wc, int fr, int fq) const {
;         const int row0 = u.pm * BM + wr * 64 + fr, col0 = u.pn * BM + wc * 32 + 8 * fq;
; #pragma unroll
;         for (int ai = 0; ai < 2; ++ai)
; #pragma unroll
;             for (int m = 0; m < 4; ++m) { const int row = row0 + ai * HALF + m * 16; float* rp = X + (size_t)row * DM + col0; const float* ip = Xin + (size_t)row * DM + col0; bf16_t* bp = XB + (size_t)row * DM + col0; float part = 0.f;
; #pragma unroll
;                 for (int bj = 0; bj < 2; ++bj) { f32x4* p = (f32x4*)(rp + bj * HALF); const f32x4* q = (const f32x4*)(ip + bj * HALF); f32x4 a = q[0], b = q[1]; a += acc[ai][bj][m][0] * scale; b += acc[ai][bj][m][1] * scale; p[0] = a; p[1] = b;
;                     *(u32x4*)(bp + bj * HALF) = (u32x4){cvtpk(a[0], a[1]), cvtpk(a[2], a[3]), cvtpk(b[0], b[1]), cvtpk(b[2], b[3])};
;                     part += (a[0] * a[0] + a[1] * a[1]) + (a[2] * a[2] + a[3] * a[3]) + (b[0] * b[0] + b[1] * b[1]) + (b[2] * b[2] + b[3] * b[3]); }
;                 part += __shfl_xor(part, 16); part += __shfl_xor(part, 32);
;                 if (fq == 0) __hip_atomic_fetch_add(SS + row, (u64)(part * SSF), __ATOMIC_RELAXED, __HIP_MEMORY_SCOPE_AGENT); }
.LBB0_1272:
	s_or_b64 exec, exec, s[16:17]
	v_add_u32_e32 v32, 0xa0, v140
	s_waitcnt lgkmcnt(0)
	v_ashrrev_i32_e32 v33, 31, v32
	v_lshlrev_b64 v[34:35], 12, v[32:33]
	v_lshl_add_u64 v[34:35], s[48:49], 0, v[34:35]
	v_lshl_add_u64 v[42:43], v[138:139], 2, v[34:35]
	v_lshlrev_b64 v[44:45], 11, v[32:33]
	v_lshl_add_u64 v[44:45], s[14:15], 0, v[44:45]
	v_lshl_add_u64 v[44:45], v[138:139], 1, v[44:45]
	s_waitcnt vmcnt(22)
	v_pk_fma_f32 v[30:31], v[30:31], 0.5, v[168:169] op_sel_hi:[1,0,1]
	v_pk_fma_f32 v[28:29], v[28:29], 0.5, v[166:167] op_sel_hi:[1,0,1]
	v_pk_fma_f32 v[26:27], v[26:27], 0.5, v[172:173] op_sel_hi:[1,0,1]
	v_pk_fma_f32 v[24:25], v[24:25], 0.5, v[170:171] op_sel_hi:[1,0,1]
	v_cvt_pk_bf16_f32 v34, v28, v29
	v_cvt_pk_bf16_f32 v35, v30, v31
	v_cvt_pk_bf16_f32 v36, v24, v25
	v_cvt_pk_bf16_f32 v37, v26, v27
	global_store_dwordx4 v[42:43], v[28:31], off
	global_store_dwordx4 v[42:43], v[24:27], off offset:16
	global_store_dwordx4 v[44:45], v[34:37], off
	s_nop 1
	v_mul_f32_e32 v29, v29, v29
	v_mul_f32_e32 v31, v31, v31
	v_mul_f32_e32 v25, v25, v25
	v_fmac_f32_e32 v29, v28, v28
	v_fmac_f32_e32 v31, v30, v30
	v_mul_f32_e32 v27, v27, v27
	v_fmac_f32_e32 v25, v24, v24
	v_add_f32_e32 v24, v29, v31
	v_fmac_f32_e32 v27, v26, v26
	v_add_f32_e32 v24, v25, v24
	v_add_f32_e32 v28, v27, v24
	v_pk_fma_f32 v[22:23], v[22:23], 0.5, v[176:177] op_sel_hi:[1,0,1]
	v_pk_fma_f32 v[20:21], v[20:21], 0.5, v[174:175] op_sel_hi:[1,0,1]
	v_pk_fma_f32 v[24:25], v[16:17], 0.5, v[178:179] op_sel_hi:[1,0,1]
	v_mul_f32_e32 v16, v21, v21
	v_mul_f32_e32 v17, v23, v23
	v_pk_fma_f32 v[26:27], v[18:19], 0.5, v[180:181] op_sel_hi:[1,0,1]
	v_mul_f32_e32 v18, v25, v25
	v_fmac_f32_e32 v16, v20, v20
	v_fmac_f32_e32 v17, v22, v22
	v_mul_f32_e32 v19, v27, v27
	v_fmac_f32_e32 v18, v24, v24
	v_add_f32_e32 v16, v16, v17
	v_add_f32_e32 v16, v18, v16
	v_fmac_f32_e32 v19, v26, v26
	v_add_f32_e32 v16, v19, v16
	v_add_f32_e32 v16, v28, v16
	ds_bpermute_b32 v17, v120, v16
	global_store_dwordx4 v[42:43], v[20:23], off offset:512
	global_store_dwordx4 v[42:43], v[24:27], off offset:528
	v_cvt_pk_bf16_f32 v18, v20, v21
	v_cvt_pk_bf16_f32 v19, v22, v23
	v_cvt_pk_bf16_f32 v20, v24, v25
	s_waitcnt lgkmcnt(0)
	v_add_f32_e32 v16, v16, v17
	ds_bpermute_b32 v17, v114, v16
	v_cvt_pk_bf16_f32 v21, v26, v27
	global_store_dwordx4 v[44:45], v[18:21], off offset:256
	s_and_saveexec_b64 s[16:17], s[40:41]
	s_cbranch_execz .LBB0_1274
	s_waitcnt lgkmcnt(0)
	v_add_f32_e32 v16, v16, v17
	v_mul_f32_e32 v16, 0x4b800000, v16
	v_trunc_f32_e32 v16, v16
	v_mul_f32_e32 v17, 0x2f800000, v16
	v_floor_f32_e32 v17, v17
	v_fmac_f32_e32 v16, 0xcf800000, v17
	v_cvt_u32_f32_e32 v16, v16
	v_cvt_u32_f32_e32 v17, v17
	v_lshl_add_u64 v[18:19], v[32:33], 3, s[18:19]
	global_atomic_add_x2 v[18:19], v[16:17], off
.LBB0_1274:
	s_or_b64 exec, exec, s[16:17]
	v_add_u32_e32 v16, 0xb0, v140
	s_waitcnt lgkmcnt(0)
	v_ashrrev_i32_e32 v17, 31, v16
	v_lshlrev_b64 v[18:19], 12, v[16:17]
	v_lshl_add_u64 v[18:19], s[48:49], 0, v[18:19]
	v_lshl_add_u64 v[26:27], v[138:139], 2, v[18:19]
	v_lshlrev_b64 v[18:19], 11, v[16:17]
	v_lshl_add_u64 v[18:19], s[14:15], 0, v[18:19]
	v_lshl_add_u64 v[28:29], v[138:139], 1, v[18:19]
	s_waitcnt vmcnt(18)
	v_pk_fma_f32 v[10:11], v[10:11], 0.5, v[188:189] op_sel_hi:[1,0,1]
	v_pk_fma_f32 v[14:15], v[14:15], 0.5, v[184:185] op_sel_hi:[1,0,1]
	v_pk_fma_f32 v[12:13], v[12:13], 0.5, v[182:183] op_sel_hi:[1,0,1]
	v_pk_fma_f32 v[8:9], v[8:9], 0.5, v[186:187] op_sel_hi:[1,0,1]
	global_store_dwordx4 v[26:27], v[12:15], off
	global_store_dwordx4 v[26:27], v[8:11], off offset:16
	v_cvt_pk_bf16_f32 v18, v12, v13
	v_mul_f32_e32 v13, v13, v13
	v_fmac_f32_e32 v13, v12, v12
	v_mul_f32_e32 v12, v15, v15
	v_cvt_pk_bf16_f32 v20, v8, v9
	v_fmac_f32_e32 v12, v14, v14
	v_mul_f32_e32 v9, v9, v9
	v_add_f32_e32 v12, v13, v12
	v_fmac_f32_e32 v9, v8, v8
	v_cvt_pk_bf16_f32 v19, v14, v15
	v_cvt_pk_bf16_f32 v21, v10, v11
	v_add_f32_e32 v8, v9, v12
	v_mul_f32_e32 v9, v11, v11
	global_store_dwordx4 v[28:29], v[18:21], off
	v_fmac_f32_e32 v9, v10, v10
	s_nop 0
	v_add_f32_e32 v18, v9, v8
	s_nop 1
	v_pk_fma_f32 v[2:3], v[2:3], 0.5, v[196:197] op_sel_hi:[1,0,1]
	v_pk_fma_f32 v[6:7], v[6:7], 0.5, v[192:193] op_sel_hi:[1,0,1]
	v_pk_fma_f32 v[4:5], v[4:5], 0.5, v[190:191] op_sel_hi:[1,0,1]
	v_pk_fma_f32 v[0:1], v[0:1], 0.5, v[194:195] op_sel_hi:[1,0,1]
	global_store_dwordx4 v[26:27], v[4:7], off offset:512
	global_store_dwordx4 v[26:27], v[0:3], off offset:528
	v_cvt_pk_bf16_f32 v8, v4, v5
	v_mul_f32_e32 v5, v5, v5
	v_fmac_f32_e32 v5, v4, v4
	v_mul_f32_e32 v4, v7, v7
	v_cvt_pk_bf16_f32 v10, v0, v1
	v_fmac_f32_e32 v4, v6, v6
	v_mul_f32_e32 v1, v1, v1
	v_add_f32_e32 v4, v5, v4
	v_fmac_f32_e32 v1, v0, v0
	v_add_f32_e32 v0, v1, v4
	v_mul_f32_e32 v1, v3, v3
	v_fmac_f32_e32 v1, v2, v2
	v_add_f32_e32 v0, v1, v0
	v_add_f32_e32 v0, v18, v0
	ds_bpermute_b32 v1, v120, v0
	v_cvt_pk_bf16_f32 v9, v6, v7
	v_cvt_pk_bf16_f32 v11, v2, v3
	global_store_dwordx4 v[28:29], v[8:11], off offset:256
	s_waitcnt lgkmcnt(0)
	v_add_f32_e32 v0, v0, v1
	ds_bpermute_b32 v1, v114, v0
	s_and_saveexec_b64 s[16:17], s[40:41]
	s_cbranch_execz .LBB0_1276
	s_waitcnt lgkmcnt(0)
	v_add_f32_e32 v0, v0, v1
	v_mul_f32_e32 v0, 0x4b800000, v0
	v_trunc_f32_e32 v0, v0
	v_mul_f32_e32 v1, 0x2f800000, v0
	v_floor_f32_e32 v1, v1
	v_fmac_f32_e32 v0, 0xcf800000, v1
	v_cvt_u32_f32_e32 v0, v0
	v_cvt_u32_f32_e32 v1, v1
	v_lshl_add_u64 v[2:3], v[16:17], 3, s[18:19]
	global_atomic_add_x2 v[2:3], v[0:1], off
